# v37
# baseline (speedup 1.0000x reference)
; DI void dsa_item(const Params& p, int b, int blk) {
;     ...
;     const int t = q0 + qq;
;     if (t >= LVALID) continue;
;     const size_t row = rowbase + t;
;     const int cnt = min((int)selcnt[qq], TOPK);
;     const u16* qptr = Aq + row * 512 + (lane & 3) * 64;
;     bf16x8 qa[8], qb[8];
;     #pragma unroll
;     for (int c = 0; c < 8; ++c) { qa[c] = ldg<bf16x8>(qptr + c * 8); qb[c] = ldg<bf16x8>(qptr + 256 + c * 8); }
;     float sc[4][8];
;     bf16x8 ka[2][8], kb[2][8];
;     bool valid[4];
;     {
;       const int ks = lane;
;       valid[0] = ks < cnt;
;       const int idx = valid[0] ? (int)sel[qq * 256 + ks] : 0;
;       const u16* kptr = Ak + (rowbase + idx) * 128;
;     ...
;     {
;       const u32x4 si = *(const u32x4*)(sel + qq * 256 + 8 * g16);
;       #pragma unroll
;       for (int j = 0; j < 8; ++j) {
;         const int ks = 8 * g16 + j;
;         const int idx = ks < cnt ? (int)((si[j >> 1] >> (16 * (j & 1))) & 0xffffu) : 0;
;         vr[j] = ldg<u32x4>(Av + (rowbase + idx) * 128 + n16 * 8);
;       }
;     }
.LBB0_1667:
	v_add_u32_e32 v66, s24, v158
	s_waitcnt vmcnt(0)
	v_add_u32_e32 v2, s36, v66
	s_movk_i32 s4, 0x2010
	v_cmp_gt_i32_e32 vcc, s4, v2
	s_and_saveexec_b64 s[4:5], vcc
	s_cbranch_execz .LBB0_1666
	v_ashrrev_i32_e32 v3, 31, v2
	v_lshl_add_u32 v0, v66, 2, 0
	v_add_u32_e32 v0, 0x1ca80, v0
	ds_read_b32 v0, v0
	v_and_b32_e32 v130, 15, v187
	v_lshlrev_b32_e32 v133, 9, v66
	v_lshl_add_u32 v133, v130, 1, v133
	v_add_u32_e32 v133, 0x10000, v133
	ds_read_u16 v18, v133
	ds_read_u16 v22, v133 offset:32
	ds_read_u16 v26, v133 offset:64
	ds_read_u16 v30, v133 offset:96
	ds_read_u16 v34, v133 offset:128
	ds_read_u16 v38, v133 offset:160
	ds_read_u16 v42, v133 offset:192
	ds_read_u16 v46, v133 offset:224
	ds_read_u16 v50, v133 offset:256
	ds_read_u16 v54, v133 offset:288
	ds_read_u16 v58, v133 offset:320
	ds_read_u16 v62, v133 offset:352
	ds_read_u16 v66, v133 offset:384
	ds_read_u16 v70, v133 offset:416
	ds_read_u16 v74, v133 offset:448
	ds_read_u16 v78, v133 offset:480
	v_lshl_add_u64 v[152:153], s[16:17], 0, v[2:3]
	v_and_b32_e32 v142, 12, v187
	v_lshlrev_b32_e32 v142, 7, v142
	v_and_b32_e32 v144, 48, v187
	v_or_b32_e32 v142, v142, v144
	v_mov_b32_e32 v143, 0
	v_mov_b32_e32 v145, 0
	v_mov_b32_e32 v134, v144
	v_lshlrev_b64 v[4:5], 10, v[152:153]
	v_lshl_add_u64 v[4:5], v[146:147], 0, v[4:5]
	v_lshl_add_u64 v[142:143], v[4:5], 0, v[142:143]
	v_xor_b32_e32 v136, 16, v187
	v_lshlrev_b32_e32 v136, 2, v136
	v_xor_b32_e32 v137, 32, v187
	v_lshlrev_b32_e32 v137, 2, v137
	v_lshrrev_b32_e32 v138, 6, v178
	v_lshlrev_b32_e32 v138, 13, v138
	v_mul_u32_u24_e32 v252, 0x210, v130
	v_add3_u32 v138, v138, v252, v156
	v_mov_b32_e32 v139, 0xf149f2ca
	v_mov_b32_e32 v141, 0
	v_mov_b32_e32 v2, 0
	v_mov_b32_e32 v3, 0
	v_mov_b32_e32 v4, 0
	v_mov_b32_e32 v5, 0
	v_mov_b32_e32 v6, 0
	v_mov_b32_e32 v7, 0
	v_mov_b32_e32 v8, 0
	v_mov_b32_e32 v9, 0
	v_mov_b32_e32 v10, 0
	v_mov_b32_e32 v11, 0
	v_mov_b32_e32 v12, 0
	v_mov_b32_e32 v13, 0
	v_mov_b32_e32 v14, 0
	v_mov_b32_e32 v15, 0
	v_mov_b32_e32 v16, 0
	v_mov_b32_e32 v17, 0
	s_mov_b32 exec_lo, 0x000f000f
	s_mov_b32 exec_hi, 0x000f000f
	global_load_dwordx4 v[2:5], v[142:143], off
	global_load_dwordx4 v[6:9], v[142:143], off offset:64
	s_mov_b32 exec_lo, 0x00f000f0
	s_mov_b32 exec_hi, 0x00f000f0
	global_load_dwordx4 v[10:13], v[142:143], off
	global_load_dwordx4 v[14:17], v[142:143], off offset:64
	s_mov_b64 exec, -1
	s_waitcnt lgkmcnt(0)
	v_min_i32_e32 v206, 0x100, v0
	v_sub_u32_e32 v131, v206, v130
	v_lshrrev_b32_e32 v132, 1, v156
	v_sub_u32_e32 v132, v206, v132
	v_readfirstlane_b32 s100, v206
	v_add_u32_e32 v242, 0xffffffc0, v188
	v_mov_b32_e32 v241, 0
	v_lshlrev_b32_e32 v253, 4, v130
	ds_read_b128 v[248:251], v242
	s_waitcnt lgkmcnt(0)
	s_cmpk_ge_i32 s100, 0x20
	s_cbranch_scc0 .Lgv0_slow
	s_mov_b32 vcc_lo, 0x0c050400
	s_mov_b32 vcc_hi, 0x0c070600
	v_perm_b32 v244, v248, v253, vcc_lo
	global_load_dwordx4 v[208:211], v244, s[12:13]
	v_perm_b32 v245, v248, v253, vcc_hi
	global_load_dwordx4 v[212:215], v245, s[12:13]
	v_perm_b32 v246, v249, v253, vcc_lo
	global_load_dwordx4 v[216:219], v246, s[12:13]
	v_perm_b32 v247, v249, v253, vcc_hi
	global_load_dwordx4 v[220:223], v247, s[12:13]
	v_perm_b32 v244, v250, v253, vcc_lo
	global_load_dwordx4 v[224:227], v244, s[12:13]
	v_perm_b32 v245, v250, v253, vcc_hi
	global_load_dwordx4 v[228:231], v245, s[12:13]
	v_perm_b32 v246, v251, v253, vcc_lo
	global_load_dwordx4 v[232:235], v246, s[12:13]
	v_perm_b32 v247, v251, v253, vcc_hi
	global_load_dwordx4 v[236:239], v247, s[12:13]
	s_branch .Lgv0_done
.Lgv0_slow:
	v_cmp_lt_i32_e32 vcc, v156, v206
	s_nop 1
	v_cndmask_b32_sdwa v240, v1, v248, vcc dst_sel:DWORD dst_unused:UNUSED_PAD src0_sel:DWORD src1_sel:WORD_0
	v_cmp_lt_i32_e32 vcc, v192, v206
	v_lshl_add_u32 v244, v240, 8, v253
	global_load_dwordx4 v[208:211], v244, s[12:13]
	v_cndmask_b32_sdwa v240, v1, v248, vcc dst_sel:DWORD dst_unused:UNUSED_PAD src0_sel:DWORD src1_sel:WORD_1
	v_cmp_lt_i32_e32 vcc, v193, v206
	v_lshl_add_u32 v245, v240, 8, v253
	global_load_dwordx4 v[212:215], v245, s[12:13]
	v_cndmask_b32_sdwa v240, v1, v249, vcc dst_sel:DWORD dst_unused:UNUSED_PAD src0_sel:DWORD src1_sel:WORD_0
	v_cmp_lt_i32_e32 vcc, v194, v206
	v_lshl_add_u32 v246, v240, 8, v253
	global_load_dwordx4 v[216:219], v246, s[12:13]
	v_cndmask_b32_sdwa v240, v1, v249, vcc dst_sel:DWORD dst_unused:UNUSED_PAD src0_sel:DWORD src1_sel:WORD_1
	v_cmp_lt_i32_e32 vcc, v157, v206
	v_lshl_add_u32 v247, v240, 8, v253
	global_load_dwordx4 v[220:223], v247, s[12:13]
	v_cndmask_b32_sdwa v240, v1, v250, vcc dst_sel:DWORD dst_unused:UNUSED_PAD src0_sel:DWORD src1_sel:WORD_0
	v_cmp_lt_i32_e32 vcc, v195, v206
	v_lshl_add_u32 v244, v240, 8, v253
	global_load_dwordx4 v[224:227], v244, s[12:13]
	v_cndmask_b32_sdwa v240, v1, v250, vcc dst_sel:DWORD dst_unused:UNUSED_PAD src0_sel:DWORD src1_sel:WORD_1
	v_cmp_lt_i32_e32 vcc, v196, v206
	v_lshl_add_u32 v245, v240, 8, v253
	global_load_dwordx4 v[228:231], v245, s[12:13]
	v_cndmask_b32_sdwa v240, v1, v251, vcc dst_sel:DWORD dst_unused:UNUSED_PAD src0_sel:DWORD src1_sel:WORD_0
	v_cmp_lt_i32_e32 vcc, v197, v206
	v_lshl_add_u32 v246, v240, 8, v253
	global_load_dwordx4 v[232:235], v246, s[12:13]
	v_cndmask_b32_sdwa v240, v1, v251, vcc dst_sel:DWORD dst_unused:UNUSED_PAD src0_sel:DWORD src1_sel:WORD_1
	v_lshl_add_u32 v247, v240, 8, v253
	global_load_dwordx4 v[236:239], v247, s[12:13]
; #define MFMA4(a, b, c)  __builtin_amdgcn_mfma_f32_4x4x4bf16_1k((a), (b), (c), 0, 0, 0)
; DI void dsa_item(const Params& p, int b, int blk) {
;     ...
;     {
;       const int ks = lane;
;       valid[0] = ks < cnt;
;       const int idx = valid[0] ? (int)sel[qq * 256 + ks] : 0;
;       const u16* kptr = Ak + (rowbase + idx) * 128;
;       #pragma unroll
;       for (int c = 0; c < 8; ++c) { ka[0][c] = ldg<bf16x8>(kptr + c * 8); kb[0][c] = ldg<bf16x8>(kptr + 64 + c * 8); }
;     }
;     #pragma unroll
;     for (int rd = 0; rd < 4; ++rd) {
;       if (rd < 3) {
;         const int ks = (rd + 1) * 64 + lane;
;         valid[rd + 1] = ks < cnt;
;         const int idx = valid[rd + 1] ? (int)sel[qq * 256 + ks] : 0;
;         const u16* kptr = Ak + (rowbase + idx) * 128;
;         #pragma unroll
;         for (int c = 0; c < 8; ++c) { ka[(rd + 1) & 1][c] = ldg<bf16x8>(kptr + c * 8); kb[(rd + 1) & 1][c] = ldg<bf16x8>(kptr + 64 + c * 8); }
;       }
;       f32x4 c0 = {0.f, 0.f, 0.f, 0.f}, c1 = {0.f, 0.f, 0.f, 0.f};
;       #pragma unroll
;       for (int c = 0; c < 8; ++c) {
;         const bf16x8 kav = ka[rd & 1][c], kbv = kb[rd & 1][c];
;         s16x4 qlo = {qa[c][0], qa[c][1], qa[c][2], qa[c][3]}, qhi = {qa[c][4], qa[c][5], qa[c][6], qa[c][7]};
;         s16x4 klo = {kav[0], kav[1], kav[2], kav[3]}, khi = {kav[4], kav[5], kav[6], kav[7]};
;         c0 = MFMA4(qlo, klo, c0); c0 = MFMA4(qhi, khi, c0);
;         s16x4 rlo = {qb[c][0], qb[c][1], qb[c][2], qb[c][3]}, rhi = {qb[c][4], qb[c][5], qb[c][6], qb[c][7]};
;         s16x4 llo = {kbv[0], kbv[1], kbv[2], kbv[3]}, lhi = {kbv[4], kbv[5], kbv[6], kbv[7]};
;         c1 = MFMA4(rlo, llo, c1); c1 = MFMA4(rhi, lhi, c1);
;       }
.Lgv0_done:
	v_cmp_lt_i32_e32 vcc, 0, v131
	s_nop 1
	v_cndmask_b32_e32 v140, v1, v18, vcc
	v_lshl_add_u32 v142, v140, 8, v134
	global_load_dwordx4 v[82:85], v142, s[14:15]
	global_load_dwordx4 v[86:89], v142, s[14:15] offset:64
	global_load_dwordx4 v[90:93], v142, s[14:15] offset:128
	global_load_dwordx4 v[94:97], v142, s[14:15] offset:192
	v_cmp_lt_i32_e32 vcc, 16, v131
	s_nop 1
	v_cndmask_b32_e32 v140, v1, v22, vcc
	v_lshl_add_u32 v144, v140, 8, v134
	global_load_dwordx4 v[98:101], v144, s[14:15]
	global_load_dwordx4 v[102:105], v144, s[14:15] offset:64
	global_load_dwordx4 v[106:109], v144, s[14:15] offset:128
	global_load_dwordx4 v[110:113], v144, s[14:15] offset:192
	v_cmp_lt_i32_e32 vcc, 32, v131
	s_nop 1
	v_cndmask_b32_e32 v140, v1, v26, vcc
	v_lshl_add_u32 v142, v140, 8, v134
	global_load_dwordx4 v[114:117], v142, s[14:15]
	global_load_dwordx4 v[118:121], v142, s[14:15] offset:64
	global_load_dwordx4 v[122:125], v142, s[14:15] offset:128
	global_load_dwordx4 v[126:129], v142, s[14:15] offset:192
	s_waitcnt vmcnt(8)
	v_mfma_f32_16x16x32_bf16 v[18:21], v[82:85], v[2:5], 0
	v_mfma_f32_16x16x32_bf16 v[18:21], v[86:89], v[6:9], v[18:21]
	v_mfma_f32_16x16x32_bf16 v[18:21], v[90:93], v[10:13], v[18:21]
	v_mfma_f32_16x16x32_bf16 v[18:21], v[94:97], v[14:17], v[18:21]
	v_cmp_lt_i32_e32 vcc, 48, v131
	s_nop 1
	v_cndmask_b32_e32 v140, v1, v30, vcc
	v_lshl_add_u32 v144, v140, 8, v134
	global_load_dwordx4 v[82:85], v144, s[14:15]
	global_load_dwordx4 v[86:89], v144, s[14:15] offset:64
	global_load_dwordx4 v[90:93], v144, s[14:15] offset:128
	global_load_dwordx4 v[94:97], v144, s[14:15] offset:192
	s_waitcnt vmcnt(8)
	v_mfma_f32_16x16x32_bf16 v[22:25], v[98:101], v[2:5], 0
	v_mfma_f32_16x16x32_bf16 v[22:25], v[102:105], v[6:9], v[22:25]
	v_mfma_f32_16x16x32_bf16 v[22:25], v[106:109], v[10:13], v[22:25]
	v_mfma_f32_16x16x32_bf16 v[22:25], v[110:113], v[14:17], v[22:25]
	v_cmp_lt_i32_e32 vcc, 64, v131
	s_nop 1
	v_cndmask_b32_e32 v140, v1, v34, vcc
	v_lshl_add_u32 v142, v140, 8, v134
	global_load_dwordx4 v[98:101], v142, s[14:15]
	global_load_dwordx4 v[102:105], v142, s[14:15] offset:64
	global_load_dwordx4 v[106:109], v142, s[14:15] offset:128
	global_load_dwordx4 v[110:113], v142, s[14:15] offset:192
	s_waitcnt vmcnt(8)
	v_mfma_f32_16x16x32_bf16 v[26:29], v[114:117], v[2:5], 0
	v_mfma_f32_16x16x32_bf16 v[26:29], v[118:121], v[6:9], v[26:29]
	v_mfma_f32_16x16x32_bf16 v[26:29], v[122:125], v[10:13], v[26:29]
	v_mfma_f32_16x16x32_bf16 v[26:29], v[126:129], v[14:17], v[26:29]
	v_cmp_lt_i32_e32 vcc, 0x50, v131
	s_nop 1
	v_cndmask_b32_e32 v140, v1, v38, vcc
	v_lshl_add_u32 v144, v140, 8, v134
	global_load_dwordx4 v[114:117], v144, s[14:15]
	global_load_dwordx4 v[118:121], v144, s[14:15] offset:64
	global_load_dwordx4 v[122:125], v144, s[14:15] offset:128
	global_load_dwordx4 v[126:129], v144, s[14:15] offset:192
	s_waitcnt vmcnt(8)
	v_mfma_f32_16x16x32_bf16 v[30:33], v[82:85], v[2:5], 0
	v_mfma_f32_16x16x32_bf16 v[30:33], v[86:89], v[6:9], v[30:33]
	v_mfma_f32_16x16x32_bf16 v[30:33], v[90:93], v[10:13], v[30:33]
	v_mfma_f32_16x16x32_bf16 v[30:33], v[94:97], v[14:17], v[30:33]
	v_cmp_lt_i32_e32 vcc, 0x60, v131
	s_nop 1
	v_cndmask_b32_e32 v140, v1, v42, vcc
	v_lshl_add_u32 v142, v140, 8, v134
	global_load_dwordx4 v[82:85], v142, s[14:15]
	global_load_dwordx4 v[86:89], v142, s[14:15] offset:64
	global_load_dwordx4 v[90:93], v142, s[14:15] offset:128
	global_load_dwordx4 v[94:97], v142, s[14:15] offset:192
	s_waitcnt vmcnt(8)
	v_mfma_f32_16x16x32_bf16 v[34:37], v[98:101], v[2:5], 0
	v_mfma_f32_16x16x32_bf16 v[34:37], v[102:105], v[6:9], v[34:37]
	v_mfma_f32_16x16x32_bf16 v[34:37], v[106:109], v[10:13], v[34:37]
	v_mfma_f32_16x16x32_bf16 v[34:37], v[110:113], v[14:17], v[34:37]
	v_cmp_lt_i32_e32 vcc, 0x70, v131
	s_nop 1
	v_cndmask_b32_e32 v140, v1, v46, vcc
	v_lshl_add_u32 v144, v140, 8, v134
	global_load_dwordx4 v[98:101], v144, s[14:15]
	global_load_dwordx4 v[102:105], v144, s[14:15] offset:64
	global_load_dwordx4 v[106:109], v144, s[14:15] offset:128
	global_load_dwordx4 v[110:113], v144, s[14:15] offset:192
	s_waitcnt vmcnt(8)
	v_mfma_f32_16x16x32_bf16 v[38:41], v[114:117], v[2:5], 0
	v_mfma_f32_16x16x32_bf16 v[38:41], v[118:121], v[6:9], v[38:41]
	v_mfma_f32_16x16x32_bf16 v[38:41], v[122:125], v[10:13], v[38:41]
	v_mfma_f32_16x16x32_bf16 v[38:41], v[126:129], v[14:17], v[38:41]
	v_cmp_lt_i32_e32 vcc, 0x80, v131
	s_nop 1
	v_cndmask_b32_e32 v140, v1, v50, vcc
	v_lshl_add_u32 v142, v140, 8, v134
	global_load_dwordx4 v[114:117], v142, s[14:15]
	global_load_dwordx4 v[118:121], v142, s[14:15] offset:64
	global_load_dwordx4 v[122:125], v142, s[14:15] offset:128
	global_load_dwordx4 v[126:129], v142, s[14:15] offset:192
	s_waitcnt vmcnt(8)
	v_mfma_f32_16x16x32_bf16 v[42:45], v[82:85], v[2:5], 0
	v_mfma_f32_16x16x32_bf16 v[42:45], v[86:89], v[6:9], v[42:45]
	v_mfma_f32_16x16x32_bf16 v[42:45], v[90:93], v[10:13], v[42:45]
	v_mfma_f32_16x16x32_bf16 v[42:45], v[94:97], v[14:17], v[42:45]
	v_cmp_lt_i32_e32 vcc, 0x90, v131
	s_nop 1
	v_cndmask_b32_e32 v140, v1, v54, vcc
	v_lshl_add_u32 v144, v140, 8, v134
	global_load_dwordx4 v[82:85], v144, s[14:15]
	global_load_dwordx4 v[86:89], v144, s[14:15] offset:64
	global_load_dwordx4 v[90:93], v144, s[14:15] offset:128
	global_load_dwordx4 v[94:97], v144, s[14:15] offset:192
	s_waitcnt vmcnt(8)
	v_mfma_f32_16x16x32_bf16 v[46:49], v[98:101], v[2:5], 0
	v_mfma_f32_16x16x32_bf16 v[46:49], v[102:105], v[6:9], v[46:49]
	v_mfma_f32_16x16x32_bf16 v[46:49], v[106:109], v[10:13], v[46:49]
	v_mfma_f32_16x16x32_bf16 v[46:49], v[110:113], v[14:17], v[46:49]
	v_cmp_lt_i32_e32 vcc, 0xa0, v131
	s_nop 1
	v_cndmask_b32_e32 v140, v1, v58, vcc
	v_lshl_add_u32 v142, v140, 8, v134
	global_load_dwordx4 v[98:101], v142, s[14:15]
	global_load_dwordx4 v[102:105], v142, s[14:15] offset:64
	global_load_dwordx4 v[106:109], v142, s[14:15] offset:128
	global_load_dwordx4 v[110:113], v142, s[14:15] offset:192
	s_waitcnt vmcnt(8)
; #define MFMA4(a, b, c)  __builtin_amdgcn_mfma_f32_4x4x4bf16_1k((a), (b), (c), 0, 0, 0)
; DI void dsa_item(const Params& p, int b, int blk) {
;     ...
;       f32x4 c0 = {0.f, 0.f, 0.f, 0.f}, c1 = {0.f, 0.f, 0.f, 0.f};
;       #pragma unroll
;       for (int c = 0; c < 8; ++c) {
;         const bf16x8 kav = ka[rd & 1][c], kbv = kb[rd & 1][c];
;         s16x4 qlo = {qa[c][0], qa[c][1], qa[c][2], qa[c][3]}, qhi = {qa[c][4], qa[c][5], qa[c][6], qa[c][7]};
;         s16x4 klo = {kav[0], kav[1], kav[2], kav[3]}, khi = {kav[4], kav[5], kav[6], kav[7]};
;         c0 = MFMA4(qlo, klo, c0); c0 = MFMA4(qhi, khi, c0);
;         s16x4 rlo = {qb[c][0], qb[c][1], qb[c][2], qb[c][3]}, rhi = {qb[c][4], qb[c][5], qb[c][6], qb[c][7]};
;         s16x4 llo = {kbv[0], kbv[1], kbv[2], kbv[3]}, lhi = {kbv[4], kbv[5], kbv[6], kbv[7]};
;         c1 = MFMA4(rlo, llo, c1); c1 = MFMA4(rhi, lhi, c1);
;       }
;       #pragma unroll
;       for (int m = 0; m < 4; ++m) { sc[rd][m] = valid[rd] ? c0[m] * SSC : -1e30f; sc[rd][4 + m] = valid[rd] ? c1[m] * SSC : -1e30f; }
;     }
;     ...
;       if (kc < 7) {
;         const u32x4 si = *(const u32x4*)(sel + qq * 256 + (kc + 1) * 32 + 8 * g16);
;         #pragma unroll
;         for (int j = 0; j < 8; ++j) {
;           const int ks = (kc + 1) * 32 + 8 * g16 + j;
;           const int idx = ks < cnt ? (int)((si[j >> 1] >> (16 * (j & 1))) & 0xffffu) : 0;
;           vr[j] = ldg<u32x4>(Av + (rowbase + idx) * 128 + n16 * 8);
;         }
;       }
	v_mfma_f32_16x16x32_bf16 v[50:53], v[114:117], v[2:5], 0
	v_mfma_f32_16x16x32_bf16 v[50:53], v[118:121], v[6:9], v[50:53]
	v_mfma_f32_16x16x32_bf16 v[50:53], v[122:125], v[10:13], v[50:53]
	v_mfma_f32_16x16x32_bf16 v[50:53], v[126:129], v[14:17], v[50:53]
	v_cmp_lt_i32_e32 vcc, 0xb0, v131
	s_nop 1
	v_cndmask_b32_e32 v140, v1, v62, vcc
	v_lshl_add_u32 v144, v140, 8, v134
	global_load_dwordx4 v[114:117], v144, s[14:15]
	global_load_dwordx4 v[118:121], v144, s[14:15] offset:64
	global_load_dwordx4 v[122:125], v144, s[14:15] offset:128
	global_load_dwordx4 v[126:129], v144, s[14:15] offset:192
	s_waitcnt vmcnt(8)
	v_mfma_f32_16x16x32_bf16 v[54:57], v[82:85], v[2:5], 0
	v_mfma_f32_16x16x32_bf16 v[54:57], v[86:89], v[6:9], v[54:57]
	v_mfma_f32_16x16x32_bf16 v[54:57], v[90:93], v[10:13], v[54:57]
	v_mfma_f32_16x16x32_bf16 v[54:57], v[94:97], v[14:17], v[54:57]
	v_cmp_lt_i32_e32 vcc, 0xc0, v131
	s_nop 1
	v_cndmask_b32_e32 v140, v1, v66, vcc
	v_lshl_add_u32 v142, v140, 8, v134
	global_load_dwordx4 v[82:85], v142, s[14:15]
	global_load_dwordx4 v[86:89], v142, s[14:15] offset:64
	global_load_dwordx4 v[90:93], v142, s[14:15] offset:128
	global_load_dwordx4 v[94:97], v142, s[14:15] offset:192
	s_waitcnt vmcnt(8)
	v_mfma_f32_16x16x32_bf16 v[58:61], v[98:101], v[2:5], 0
	v_mfma_f32_16x16x32_bf16 v[58:61], v[102:105], v[6:9], v[58:61]
	v_mfma_f32_16x16x32_bf16 v[58:61], v[106:109], v[10:13], v[58:61]
	v_mfma_f32_16x16x32_bf16 v[58:61], v[110:113], v[14:17], v[58:61]
	v_cmp_lt_i32_e32 vcc, 0xd0, v131
	s_nop 1
	v_cndmask_b32_e32 v140, v1, v70, vcc
	v_lshl_add_u32 v144, v140, 8, v134
	global_load_dwordx4 v[98:101], v144, s[14:15]
	global_load_dwordx4 v[102:105], v144, s[14:15] offset:64
	global_load_dwordx4 v[106:109], v144, s[14:15] offset:128
	global_load_dwordx4 v[110:113], v144, s[14:15] offset:192
	s_waitcnt vmcnt(8)
	v_mfma_f32_16x16x32_bf16 v[62:65], v[114:117], v[2:5], 0
	v_mfma_f32_16x16x32_bf16 v[62:65], v[118:121], v[6:9], v[62:65]
	v_mfma_f32_16x16x32_bf16 v[62:65], v[122:125], v[10:13], v[62:65]
	v_mfma_f32_16x16x32_bf16 v[62:65], v[126:129], v[14:17], v[62:65]
	v_cmp_lt_i32_e32 vcc, 0xe0, v131
	s_nop 1
	v_cndmask_b32_e32 v140, v1, v74, vcc
	v_lshl_add_u32 v142, v140, 8, v134
	global_load_dwordx4 v[114:117], v142, s[14:15]
	global_load_dwordx4 v[118:121], v142, s[14:15] offset:64
	global_load_dwordx4 v[122:125], v142, s[14:15] offset:128
	global_load_dwordx4 v[126:129], v142, s[14:15] offset:192
	s_waitcnt vmcnt(8)
	v_mfma_f32_16x16x32_bf16 v[66:69], v[82:85], v[2:5], 0
	v_mfma_f32_16x16x32_bf16 v[66:69], v[86:89], v[6:9], v[66:69]
	v_mfma_f32_16x16x32_bf16 v[66:69], v[90:93], v[10:13], v[66:69]
	v_mfma_f32_16x16x32_bf16 v[66:69], v[94:97], v[14:17], v[66:69]
	v_cmp_lt_i32_e32 vcc, 0xf0, v131
	s_nop 1
	v_cndmask_b32_e32 v140, v1, v78, vcc
	v_lshl_add_u32 v144, v140, 8, v134
	global_load_dwordx4 v[82:85], v144, s[14:15]
	global_load_dwordx4 v[86:89], v144, s[14:15] offset:64
	global_load_dwordx4 v[90:93], v144, s[14:15] offset:128
	global_load_dwordx4 v[94:97], v144, s[14:15] offset:192
	s_waitcnt vmcnt(8)
	v_mfma_f32_16x16x32_bf16 v[70:73], v[98:101], v[2:5], 0
	v_mfma_f32_16x16x32_bf16 v[70:73], v[102:105], v[6:9], v[70:73]
	v_mfma_f32_16x16x32_bf16 v[70:73], v[106:109], v[10:13], v[70:73]
	v_mfma_f32_16x16x32_bf16 v[70:73], v[110:113], v[14:17], v[70:73]
	s_waitcnt vmcnt(4)
	v_mfma_f32_16x16x32_bf16 v[74:77], v[114:117], v[2:5], 0
	v_mfma_f32_16x16x32_bf16 v[74:77], v[118:121], v[6:9], v[74:77]
	v_mfma_f32_16x16x32_bf16 v[74:77], v[122:125], v[10:13], v[74:77]
	v_mfma_f32_16x16x32_bf16 v[74:77], v[126:129], v[14:17], v[74:77]
	s_waitcnt vmcnt(0)
	v_mfma_f32_16x16x32_bf16 v[78:81], v[82:85], v[2:5], 0
	v_mfma_f32_16x16x32_bf16 v[78:81], v[86:89], v[6:9], v[78:81]
	v_mfma_f32_16x16x32_bf16 v[78:81], v[90:93], v[10:13], v[78:81]
	v_mfma_f32_16x16x32_bf16 v[78:81], v[94:97], v[14:17], v[78:81]
	v_mov_b32_e32 v8, v132
	v_mov_b32_e32 v9, v136
	v_mov_b32_e32 v10, v137
	ds_read_b128 v[12:15], v242 offset:64
	s_waitcnt lgkmcnt(0)
	s_cmpk_ge_i32 s100, 0x40
	s_cbranch_scc0 .Lgv1_slow
	s_mov_b32 vcc_lo, 0x0c050400
	s_mov_b32 vcc_hi, 0x0c070600
	v_perm_b32 v244, v12, v253, vcc_lo
	global_load_dwordx4 v[106:109], v244, s[12:13]
	v_perm_b32 v245, v12, v253, vcc_hi
	global_load_dwordx4 v[110:113], v245, s[12:13]
	v_perm_b32 v246, v13, v253, vcc_lo
	global_load_dwordx4 v[114:117], v246, s[12:13]
	v_perm_b32 v247, v13, v253, vcc_hi
	global_load_dwordx4 v[118:121], v247, s[12:13]
	v_perm_b32 v244, v14, v253, vcc_lo
	global_load_dwordx4 v[122:125], v244, s[12:13]
	v_perm_b32 v245, v14, v253, vcc_hi
	global_load_dwordx4 v[126:129], v245, s[12:13]
	v_perm_b32 v246, v15, v253, vcc_lo
	global_load_dwordx4 v[130:133], v246, s[12:13]
	v_perm_b32 v247, v15, v253, vcc_hi
	global_load_dwordx4 v[134:137], v247, s[12:13]
	s_branch .Lgv1_done
; DI void dsa_item(const Params& p, int b, int blk) {
;     ...
;       for (int m = 0; m < 4; ++m) { sc[rd][m] = valid[rd] ? c0[m] * SSC : -1e30f; sc[rd][4 + m] = valid[rd] ? c1[m] * SSC : -1e30f; }
;     }
;     ...
;       if (kc < 7) {
;         const u32x4 si = *(const u32x4*)(sel + qq * 256 + (kc + 1) * 32 + 8 * g16);
;         #pragma unroll
;         for (int j = 0; j < 8; ++j) {
;           const int ks = (kc + 1) * 32 + 8 * g16 + j;
;           const int idx = ks < cnt ? (int)((si[j >> 1] >> (16 * (j & 1))) & 0xffffu) : 0;
;           vr[j] = ldg<u32x4>(Av + (rowbase + idx) * 128 + n16 * 8);
;         }
;       }
.Lgv1_slow:
	v_add_u32_e32 v243, 0xffffffe0, v206
	v_cmp_lt_i32_e32 vcc, v156, v243
	s_nop 1
	v_cndmask_b32_sdwa v240, v1, v12, vcc dst_sel:DWORD dst_unused:UNUSED_PAD src0_sel:DWORD src1_sel:WORD_0
	v_cmp_lt_i32_e32 vcc, v192, v243
	v_lshl_add_u32 v244, v240, 8, v253
	global_load_dwordx4 v[106:109], v244, s[12:13]
	v_cndmask_b32_sdwa v240, v1, v12, vcc dst_sel:DWORD dst_unused:UNUSED_PAD src0_sel:DWORD src1_sel:WORD_1
	v_cmp_lt_i32_e32 vcc, v193, v243
	v_lshl_add_u32 v245, v240, 8, v253
	global_load_dwordx4 v[110:113], v245, s[12:13]
	v_cndmask_b32_sdwa v240, v1, v13, vcc dst_sel:DWORD dst_unused:UNUSED_PAD src0_sel:DWORD src1_sel:WORD_0
	v_cmp_lt_i32_e32 vcc, v194, v243
	v_lshl_add_u32 v246, v240, 8, v253
	global_load_dwordx4 v[114:117], v246, s[12:13]
	v_cndmask_b32_sdwa v240, v1, v13, vcc dst_sel:DWORD dst_unused:UNUSED_PAD src0_sel:DWORD src1_sel:WORD_1
	v_cmp_lt_i32_e32 vcc, v157, v243
	v_lshl_add_u32 v247, v240, 8, v253
	global_load_dwordx4 v[118:121], v247, s[12:13]
	v_cndmask_b32_sdwa v240, v1, v14, vcc dst_sel:DWORD dst_unused:UNUSED_PAD src0_sel:DWORD src1_sel:WORD_0
	v_cmp_lt_i32_e32 vcc, v195, v243
	v_lshl_add_u32 v244, v240, 8, v253
	global_load_dwordx4 v[122:125], v244, s[12:13]
	v_cndmask_b32_sdwa v240, v1, v14, vcc dst_sel:DWORD dst_unused:UNUSED_PAD src0_sel:DWORD src1_sel:WORD_1
	v_cmp_lt_i32_e32 vcc, v196, v243
	v_lshl_add_u32 v245, v240, 8, v253
	global_load_dwordx4 v[126:129], v245, s[12:13]
	v_cndmask_b32_sdwa v240, v1, v15, vcc dst_sel:DWORD dst_unused:UNUSED_PAD src0_sel:DWORD src1_sel:WORD_0
	v_cmp_lt_i32_e32 vcc, v197, v243
	v_lshl_add_u32 v246, v240, 8, v253
	global_load_dwordx4 v[130:133], v246, s[12:13]
	v_cndmask_b32_sdwa v240, v1, v15, vcc dst_sel:DWORD dst_unused:UNUSED_PAD src0_sel:DWORD src1_sel:WORD_1
	v_lshl_add_u32 v247, v240, 8, v253
	global_load_dwordx4 v[134:137], v247, s[12:13]
.Lgv1_done:
	v_mul_f32_e32 v18, 0x3e38aa3b, v18
	v_mul_f32_e32 v19, 0x3e38aa3b, v19
	v_mul_f32_e32 v20, 0x3e38aa3b, v20
	v_mul_f32_e32 v21, 0x3e38aa3b, v21
	v_mul_f32_e32 v22, 0x3e38aa3b, v22
	v_mul_f32_e32 v23, 0x3e38aa3b, v23
	v_mul_f32_e32 v24, 0x3e38aa3b, v24
	v_mul_f32_e32 v25, 0x3e38aa3b, v25
	v_mul_f32_e32 v26, 0x3e38aa3b, v26
	v_mul_f32_e32 v27, 0x3e38aa3b, v27
	v_mul_f32_e32 v28, 0x3e38aa3b, v28
	v_mul_f32_e32 v29, 0x3e38aa3b, v29
	v_mul_f32_e32 v30, 0x3e38aa3b, v30
	v_mul_f32_e32 v31, 0x3e38aa3b, v31
	v_mul_f32_e32 v32, 0x3e38aa3b, v32
	v_mul_f32_e32 v33, 0x3e38aa3b, v33
	v_mul_f32_e32 v34, 0x3e38aa3b, v34
	v_mul_f32_e32 v35, 0x3e38aa3b, v35
	v_mul_f32_e32 v36, 0x3e38aa3b, v36
	v_mul_f32_e32 v37, 0x3e38aa3b, v37
	v_mul_f32_e32 v38, 0x3e38aa3b, v38
	v_mul_f32_e32 v39, 0x3e38aa3b, v39
	v_mul_f32_e32 v40, 0x3e38aa3b, v40
	v_mul_f32_e32 v41, 0x3e38aa3b, v41
	v_mul_f32_e32 v42, 0x3e38aa3b, v42
	v_mul_f32_e32 v43, 0x3e38aa3b, v43
	v_mul_f32_e32 v44, 0x3e38aa3b, v44
	v_mul_f32_e32 v45, 0x3e38aa3b, v45
	v_mul_f32_e32 v46, 0x3e38aa3b, v46
	v_mul_f32_e32 v47, 0x3e38aa3b, v47
	v_mul_f32_e32 v48, 0x3e38aa3b, v48
	v_mul_f32_e32 v49, 0x3e38aa3b, v49
	v_mul_f32_e32 v50, 0x3e38aa3b, v50
	v_mul_f32_e32 v51, 0x3e38aa3b, v51
	v_mul_f32_e32 v52, 0x3e38aa3b, v52
	v_mul_f32_e32 v53, 0x3e38aa3b, v53
	v_mul_f32_e32 v54, 0x3e38aa3b, v54
	v_mul_f32_e32 v55, 0x3e38aa3b, v55
	v_mul_f32_e32 v56, 0x3e38aa3b, v56
	v_mul_f32_e32 v57, 0x3e38aa3b, v57
	v_mul_f32_e32 v58, 0x3e38aa3b, v58
	v_mul_f32_e32 v59, 0x3e38aa3b, v59
	v_mul_f32_e32 v60, 0x3e38aa3b, v60
	v_mul_f32_e32 v61, 0x3e38aa3b, v61
	v_mul_f32_e32 v62, 0x3e38aa3b, v62
	v_mul_f32_e32 v63, 0x3e38aa3b, v63
	v_mul_f32_e32 v64, 0x3e38aa3b, v64
	v_mul_f32_e32 v65, 0x3e38aa3b, v65
	v_mul_f32_e32 v66, 0x3e38aa3b, v66
	v_mul_f32_e32 v67, 0x3e38aa3b, v67
	v_mul_f32_e32 v68, 0x3e38aa3b, v68
	v_mul_f32_e32 v69, 0x3e38aa3b, v69
	v_mul_f32_e32 v70, 0x3e38aa3b, v70
	v_mul_f32_e32 v71, 0x3e38aa3b, v71
	v_mul_f32_e32 v72, 0x3e38aa3b, v72
	v_mul_f32_e32 v73, 0x3e38aa3b, v73
	v_mul_f32_e32 v74, 0x3e38aa3b, v74
	v_mul_f32_e32 v75, 0x3e38aa3b, v75
	v_mul_f32_e32 v76, 0x3e38aa3b, v76
	v_mul_f32_e32 v77, 0x3e38aa3b, v77
	v_mul_f32_e32 v78, 0x3e38aa3b, v78
	v_mul_f32_e32 v79, 0x3e38aa3b, v79
	v_mul_f32_e32 v80, 0x3e38aa3b, v80
	v_mul_f32_e32 v81, 0x3e38aa3b, v81
	s_cmpk_ge_i32 s100, 0x100
	s_cbranch_scc1 .Lqk_nomask
	v_cmp_lt_i32_e32 vcc, 0, v8
	s_nop 1
	v_cndmask_b32_e32 v18, v139, v18, vcc
	v_cmp_lt_i32_e32 vcc, 1, v8
	s_nop 1
	v_cndmask_b32_e32 v19, v139, v19, vcc
	v_cmp_lt_i32_e32 vcc, 2, v8
	s_nop 1
	v_cndmask_b32_e32 v20, v139, v20, vcc
	v_cmp_lt_i32_e32 vcc, 3, v8
	s_nop 1
	v_cndmask_b32_e32 v21, v139, v21, vcc
	v_cmp_lt_i32_e32 vcc, 16, v8
	s_nop 1
	v_cndmask_b32_e32 v22, v139, v22, vcc
	v_cmp_lt_i32_e32 vcc, 17, v8
	s_nop 1
	v_cndmask_b32_e32 v23, v139, v23, vcc
	v_cmp_lt_i32_e32 vcc, 18, v8
	s_nop 1
	v_cndmask_b32_e32 v24, v139, v24, vcc
	v_cmp_lt_i32_e32 vcc, 19, v8
	s_nop 1
	v_cndmask_b32_e32 v25, v139, v25, vcc
	v_cmp_lt_i32_e32 vcc, 32, v8
	s_nop 1
	v_cndmask_b32_e32 v26, v139, v26, vcc
	v_cmp_lt_i32_e32 vcc, 33, v8
	s_nop 1
	v_cndmask_b32_e32 v27, v139, v27, vcc
	v_cmp_lt_i32_e32 vcc, 34, v8
	s_nop 1
	v_cndmask_b32_e32 v28, v139, v28, vcc
	v_cmp_lt_i32_e32 vcc, 35, v8
	s_nop 1
	v_cndmask_b32_e32 v29, v139, v29, vcc
	v_cmp_lt_i32_e32 vcc, 48, v8
	s_nop 1
	v_cndmask_b32_e32 v30, v139, v30, vcc
	v_cmp_lt_i32_e32 vcc, 49, v8
	s_nop 1
	v_cndmask_b32_e32 v31, v139, v31, vcc
	v_cmp_lt_i32_e32 vcc, 50, v8
	s_nop 1
	v_cndmask_b32_e32 v32, v139, v32, vcc
	v_cmp_lt_i32_e32 vcc, 51, v8
	s_nop 1
	v_cndmask_b32_e32 v33, v139, v33, vcc
	v_cmp_lt_i32_e32 vcc, 64, v8
	s_nop 1
	v_cndmask_b32_e32 v34, v139, v34, vcc
	v_cmp_lt_i32_e32 vcc, 0x41, v8
	s_nop 1
	v_cndmask_b32_e32 v35, v139, v35, vcc
; DI void dsa_item(const Params& p, int b, int blk) {
;     ...
;       for (int m = 0; m < 4; ++m) { sc[rd][m] = valid[rd] ? c0[m] * SSC : -1e30f; sc[rd][4 + m] = valid[rd] ? c1[m] * SSC : -1e30f; }
;     }
;     float inv[8];
;     #pragma unroll
;     for (int m = 0; m < 8; ++m) {
;       float mx = fmaxf(fmaxf(sc[0][m], sc[1][m]), fmaxf(sc[2][m], sc[3][m]));
;       mx = wave_max(mx);
	v_cmp_lt_i32_e32 vcc, 0x42, v8
	s_nop 1
	v_cndmask_b32_e32 v36, v139, v36, vcc
	v_cmp_lt_i32_e32 vcc, 0x43, v8
	s_nop 1
	v_cndmask_b32_e32 v37, v139, v37, vcc
	v_cmp_lt_i32_e32 vcc, 0x50, v8
	s_nop 1
	v_cndmask_b32_e32 v38, v139, v38, vcc
	v_cmp_lt_i32_e32 vcc, 0x51, v8
	s_nop 1
	v_cndmask_b32_e32 v39, v139, v39, vcc
	v_cmp_lt_i32_e32 vcc, 0x52, v8
	s_nop 1
	v_cndmask_b32_e32 v40, v139, v40, vcc
	v_cmp_lt_i32_e32 vcc, 0x53, v8
	s_nop 1
	v_cndmask_b32_e32 v41, v139, v41, vcc
	v_cmp_lt_i32_e32 vcc, 0x60, v8
	s_nop 1
	v_cndmask_b32_e32 v42, v139, v42, vcc
	v_cmp_lt_i32_e32 vcc, 0x61, v8
	s_nop 1
	v_cndmask_b32_e32 v43, v139, v43, vcc
	v_cmp_lt_i32_e32 vcc, 0x62, v8
	s_nop 1
	v_cndmask_b32_e32 v44, v139, v44, vcc
	v_cmp_lt_i32_e32 vcc, 0x63, v8
	s_nop 1
	v_cndmask_b32_e32 v45, v139, v45, vcc
	v_cmp_lt_i32_e32 vcc, 0x70, v8
	s_nop 1
	v_cndmask_b32_e32 v46, v139, v46, vcc
	v_cmp_lt_i32_e32 vcc, 0x71, v8
	s_nop 1
	v_cndmask_b32_e32 v47, v139, v47, vcc
	v_cmp_lt_i32_e32 vcc, 0x72, v8
	s_nop 1
	v_cndmask_b32_e32 v48, v139, v48, vcc
	v_cmp_lt_i32_e32 vcc, 0x73, v8
	s_nop 1
	v_cndmask_b32_e32 v49, v139, v49, vcc
	v_cmp_lt_i32_e32 vcc, 0x80, v8
	s_nop 1
	v_cndmask_b32_e32 v50, v139, v50, vcc
	v_cmp_lt_i32_e32 vcc, 0x81, v8
	s_nop 1
	v_cndmask_b32_e32 v51, v139, v51, vcc
	v_cmp_lt_i32_e32 vcc, 0x82, v8
	s_nop 1
	v_cndmask_b32_e32 v52, v139, v52, vcc
	v_cmp_lt_i32_e32 vcc, 0x83, v8
	s_nop 1
	v_cndmask_b32_e32 v53, v139, v53, vcc
	v_cmp_lt_i32_e32 vcc, 0x90, v8
	s_nop 1
	v_cndmask_b32_e32 v54, v139, v54, vcc
	v_cmp_lt_i32_e32 vcc, 0x91, v8
	s_nop 1
	v_cndmask_b32_e32 v55, v139, v55, vcc
	v_cmp_lt_i32_e32 vcc, 0x92, v8
	s_nop 1
	v_cndmask_b32_e32 v56, v139, v56, vcc
	v_cmp_lt_i32_e32 vcc, 0x93, v8
	s_nop 1
	v_cndmask_b32_e32 v57, v139, v57, vcc
	v_cmp_lt_i32_e32 vcc, 0xa0, v8
	s_nop 1
	v_cndmask_b32_e32 v58, v139, v58, vcc
	v_cmp_lt_i32_e32 vcc, 0xa1, v8
	s_nop 1
	v_cndmask_b32_e32 v59, v139, v59, vcc
	v_cmp_lt_i32_e32 vcc, 0xa2, v8
	s_nop 1
	v_cndmask_b32_e32 v60, v139, v60, vcc
	v_cmp_lt_i32_e32 vcc, 0xa3, v8
	s_nop 1
	v_cndmask_b32_e32 v61, v139, v61, vcc
	v_cmp_lt_i32_e32 vcc, 0xb0, v8
	s_nop 1
	v_cndmask_b32_e32 v62, v139, v62, vcc
	v_cmp_lt_i32_e32 vcc, 0xb1, v8
	s_nop 1
	v_cndmask_b32_e32 v63, v139, v63, vcc
	v_cmp_lt_i32_e32 vcc, 0xb2, v8
	s_nop 1
	v_cndmask_b32_e32 v64, v139, v64, vcc
	v_cmp_lt_i32_e32 vcc, 0xb3, v8
	s_nop 1
	v_cndmask_b32_e32 v65, v139, v65, vcc
	v_cmp_lt_i32_e32 vcc, 0xc0, v8
	s_nop 1
	v_cndmask_b32_e32 v66, v139, v66, vcc
	v_cmp_lt_i32_e32 vcc, 0xc1, v8
	s_nop 1
	v_cndmask_b32_e32 v67, v139, v67, vcc
	v_cmp_lt_i32_e32 vcc, 0xc2, v8
	s_nop 1
	v_cndmask_b32_e32 v68, v139, v68, vcc
	v_cmp_lt_i32_e32 vcc, 0xc3, v8
	s_nop 1
	v_cndmask_b32_e32 v69, v139, v69, vcc
	v_cmp_lt_i32_e32 vcc, 0xd0, v8
	s_nop 1
	v_cndmask_b32_e32 v70, v139, v70, vcc
	v_cmp_lt_i32_e32 vcc, 0xd1, v8
	s_nop 1
	v_cndmask_b32_e32 v71, v139, v71, vcc
	v_cmp_lt_i32_e32 vcc, 0xd2, v8
	s_nop 1
	v_cndmask_b32_e32 v72, v139, v72, vcc
	v_cmp_lt_i32_e32 vcc, 0xd3, v8
	s_nop 1
	v_cndmask_b32_e32 v73, v139, v73, vcc
	v_cmp_lt_i32_e32 vcc, 0xe0, v8
	s_nop 1
	v_cndmask_b32_e32 v74, v139, v74, vcc
	v_cmp_lt_i32_e32 vcc, 0xe1, v8
	s_nop 1
	v_cndmask_b32_e32 v75, v139, v75, vcc
	v_cmp_lt_i32_e32 vcc, 0xe2, v8
	s_nop 1
	v_cndmask_b32_e32 v76, v139, v76, vcc
	v_cmp_lt_i32_e32 vcc, 0xe3, v8
	s_nop 1
	v_cndmask_b32_e32 v77, v139, v77, vcc
	v_cmp_lt_i32_e32 vcc, 0xf0, v8
	s_nop 1
	v_cndmask_b32_e32 v78, v139, v78, vcc
	v_cmp_lt_i32_e32 vcc, 0xf1, v8
	s_nop 1
	v_cndmask_b32_e32 v79, v139, v79, vcc
	v_cmp_lt_i32_e32 vcc, 0xf2, v8
	s_nop 1
	v_cndmask_b32_e32 v80, v139, v80, vcc
	v_cmp_lt_i32_e32 vcc, 0xf3, v8
	s_nop 1
	v_cndmask_b32_e32 v81, v139, v81, vcc
.Lqk_nomask:
	v_max3_f32 v0, v18, v19, v20
	v_max3_f32 v0, v0, v21, v22
	v_max3_f32 v0, v0, v23, v24
	v_max3_f32 v0, v0, v25, v26
	v_max3_f32 v0, v0, v27, v28
	v_max3_f32 v0, v0, v29, v30
	v_max3_f32 v0, v0, v31, v32
	v_max3_f32 v0, v0, v33, v34
	v_max3_f32 v0, v0, v35, v36
	v_max3_f32 v0, v0, v37, v38
	v_max3_f32 v0, v0, v39, v40
	v_max3_f32 v0, v0, v41, v42
	v_max3_f32 v0, v0, v43, v44
	v_max3_f32 v0, v0, v45, v46
	v_max3_f32 v0, v0, v47, v48
	v_max3_f32 v0, v0, v49, v50
	v_max3_f32 v0, v0, v51, v52
	v_max3_f32 v0, v0, v53, v54
	v_max3_f32 v0, v0, v55, v56
	v_max3_f32 v0, v0, v57, v58
	v_max3_f32 v0, v0, v59, v60
	v_max3_f32 v0, v0, v61, v62
	v_max3_f32 v0, v0, v63, v64
	v_max3_f32 v0, v0, v65, v66
	v_max3_f32 v0, v0, v67, v68
	v_max3_f32 v0, v0, v69, v70
	v_max3_f32 v0, v0, v71, v72
	v_max3_f32 v0, v0, v73, v74
	v_max3_f32 v0, v0, v75, v76
	v_max3_f32 v0, v0, v77, v78
	v_max3_f32 v0, v0, v79, v80
	v_max_f32_e32 v0, v0, v81
	ds_bpermute_b32 v252, v9, v0
	s_waitcnt lgkmcnt(0)
	v_max_f32_e32 v0, v0, v252
	ds_bpermute_b32 v252, v10, v0
	s_waitcnt lgkmcnt(0)
; DI float fast_exp2(float x) { return __builtin_amdgcn_exp2f(x); }
; DI void dsa_item(const Params& p, int b, int blk) {
;     ...
;     for (int m = 0; m < 8; ++m) {
;       float mx = fmaxf(fmaxf(sc[0][m], sc[1][m]), fmaxf(sc[2][m], sc[3][m]));
;       mx = wave_max(mx);
;       float s = 0.f;
;       #pragma unroll
;       for (int rd = 0; rd < 4; ++rd) { sc[rd][m] = fast_exp2(sc[rd][m] - mx); s += sc[rd][m]; }
;       s = wave_sum(s);
;       inv[m] = 1.f / s;
	v_max_f32_e32 v0, v0, v252
	v_sub_f32_e32 v18, v18, v0
	v_sub_f32_e32 v19, v19, v0
	v_sub_f32_e32 v20, v20, v0
	v_sub_f32_e32 v21, v21, v0
	v_sub_f32_e32 v22, v22, v0
	v_sub_f32_e32 v23, v23, v0
	v_sub_f32_e32 v24, v24, v0
	v_sub_f32_e32 v25, v25, v0
	v_sub_f32_e32 v26, v26, v0
	v_sub_f32_e32 v27, v27, v0
	v_sub_f32_e32 v28, v28, v0
	v_sub_f32_e32 v29, v29, v0
	v_sub_f32_e32 v30, v30, v0
	v_sub_f32_e32 v31, v31, v0
	v_sub_f32_e32 v32, v32, v0
	v_sub_f32_e32 v33, v33, v0
	v_sub_f32_e32 v34, v34, v0
	v_sub_f32_e32 v35, v35, v0
	v_sub_f32_e32 v36, v36, v0
	v_sub_f32_e32 v37, v37, v0
	v_sub_f32_e32 v38, v38, v0
	v_sub_f32_e32 v39, v39, v0
	v_sub_f32_e32 v40, v40, v0
	v_sub_f32_e32 v41, v41, v0
	v_sub_f32_e32 v42, v42, v0
	v_sub_f32_e32 v43, v43, v0
	v_sub_f32_e32 v44, v44, v0
	v_sub_f32_e32 v45, v45, v0
	v_sub_f32_e32 v46, v46, v0
	v_sub_f32_e32 v47, v47, v0
	v_sub_f32_e32 v48, v48, v0
	v_sub_f32_e32 v49, v49, v0
	v_sub_f32_e32 v50, v50, v0
	v_sub_f32_e32 v51, v51, v0
	v_sub_f32_e32 v52, v52, v0
	v_sub_f32_e32 v53, v53, v0
	v_sub_f32_e32 v54, v54, v0
	v_sub_f32_e32 v55, v55, v0
	v_sub_f32_e32 v56, v56, v0
	v_sub_f32_e32 v57, v57, v0
	v_sub_f32_e32 v58, v58, v0
	v_sub_f32_e32 v59, v59, v0
	v_sub_f32_e32 v60, v60, v0
	v_sub_f32_e32 v61, v61, v0
	v_sub_f32_e32 v62, v62, v0
	v_sub_f32_e32 v63, v63, v0
	v_sub_f32_e32 v64, v64, v0
	v_sub_f32_e32 v65, v65, v0
	v_sub_f32_e32 v66, v66, v0
	v_sub_f32_e32 v67, v67, v0
	v_sub_f32_e32 v68, v68, v0
	v_sub_f32_e32 v69, v69, v0
	v_sub_f32_e32 v70, v70, v0
	v_sub_f32_e32 v71, v71, v0
	v_sub_f32_e32 v72, v72, v0
	v_sub_f32_e32 v73, v73, v0
	v_sub_f32_e32 v74, v74, v0
	v_sub_f32_e32 v75, v75, v0
	v_sub_f32_e32 v76, v76, v0
	v_sub_f32_e32 v77, v77, v0
	v_sub_f32_e32 v78, v78, v0
	v_sub_f32_e32 v79, v79, v0
	v_sub_f32_e32 v80, v80, v0
	v_sub_f32_e32 v81, v81, v0
	v_exp_f32_e32 v18, v18
	v_exp_f32_e32 v19, v19
	v_exp_f32_e32 v20, v20
	v_exp_f32_e32 v21, v21
	v_exp_f32_e32 v22, v22
	v_exp_f32_e32 v23, v23
	v_exp_f32_e32 v24, v24
	v_exp_f32_e32 v25, v25
	v_exp_f32_e32 v26, v26
	v_exp_f32_e32 v27, v27
	v_exp_f32_e32 v28, v28
	v_exp_f32_e32 v29, v29
	v_exp_f32_e32 v30, v30
	v_exp_f32_e32 v31, v31
	v_exp_f32_e32 v32, v32
	v_exp_f32_e32 v33, v33
	v_exp_f32_e32 v34, v34
	v_exp_f32_e32 v35, v35
	v_exp_f32_e32 v36, v36
	v_exp_f32_e32 v37, v37
	v_exp_f32_e32 v38, v38
	v_exp_f32_e32 v39, v39
	v_exp_f32_e32 v40, v40
	v_exp_f32_e32 v41, v41
	v_exp_f32_e32 v42, v42
	v_exp_f32_e32 v43, v43
	v_exp_f32_e32 v44, v44
	v_exp_f32_e32 v45, v45
	v_exp_f32_e32 v46, v46
	v_exp_f32_e32 v47, v47
	v_exp_f32_e32 v48, v48
	v_exp_f32_e32 v49, v49
	v_exp_f32_e32 v50, v50
	v_exp_f32_e32 v51, v51
	v_exp_f32_e32 v52, v52
	v_exp_f32_e32 v53, v53
	v_exp_f32_e32 v54, v54
	v_exp_f32_e32 v55, v55
	v_exp_f32_e32 v56, v56
	v_exp_f32_e32 v57, v57
	v_exp_f32_e32 v58, v58
	v_exp_f32_e32 v59, v59
	v_exp_f32_e32 v60, v60
	v_exp_f32_e32 v61, v61
	v_exp_f32_e32 v62, v62
	v_exp_f32_e32 v63, v63
	v_exp_f32_e32 v64, v64
	v_exp_f32_e32 v65, v65
	v_exp_f32_e32 v66, v66
	v_exp_f32_e32 v67, v67
	v_exp_f32_e32 v68, v68
	v_exp_f32_e32 v69, v69
	v_exp_f32_e32 v70, v70
	v_exp_f32_e32 v71, v71
	v_exp_f32_e32 v72, v72
	v_exp_f32_e32 v73, v73
	v_exp_f32_e32 v74, v74
	v_exp_f32_e32 v75, v75
	v_exp_f32_e32 v76, v76
	v_exp_f32_e32 v77, v77
	v_exp_f32_e32 v78, v78
	v_exp_f32_e32 v79, v79
	v_exp_f32_e32 v80, v80
	v_exp_f32_e32 v81, v81
	s_nop 0
	v_add_f32_e32 v253, v18, v19
	v_add_f32_e32 v253, v253, v20
	v_add_f32_e32 v253, v253, v21
	v_add_f32_e32 v253, v253, v22
	v_add_f32_e32 v253, v253, v23
	v_add_f32_e32 v253, v253, v24
	v_add_f32_e32 v253, v253, v25
	v_add_f32_e32 v253, v253, v26
	v_add_f32_e32 v253, v253, v27
	v_add_f32_e32 v253, v253, v28
	v_add_f32_e32 v253, v253, v29
	v_add_f32_e32 v253, v253, v30
	v_add_f32_e32 v253, v253, v31
	v_add_f32_e32 v253, v253, v32
	v_add_f32_e32 v253, v253, v33
	v_add_f32_e32 v253, v253, v34
	v_add_f32_e32 v253, v253, v35
	v_add_f32_e32 v253, v253, v36
	v_add_f32_e32 v253, v253, v37
	v_add_f32_e32 v253, v253, v38
	v_add_f32_e32 v253, v253, v39
	v_add_f32_e32 v253, v253, v40
	v_add_f32_e32 v253, v253, v41
	v_add_f32_e32 v253, v253, v42
	v_add_f32_e32 v253, v253, v43
	v_add_f32_e32 v253, v253, v44
	v_add_f32_e32 v253, v253, v45
	v_add_f32_e32 v253, v253, v46
	v_add_f32_e32 v253, v253, v47
	v_add_f32_e32 v253, v253, v48
	v_add_f32_e32 v253, v253, v49
	v_add_f32_e32 v253, v253, v50
	v_add_f32_e32 v253, v253, v51
	v_add_f32_e32 v253, v253, v52
	v_add_f32_e32 v253, v253, v53
	v_add_f32_e32 v253, v253, v54
	v_add_f32_e32 v253, v253, v55
	v_add_f32_e32 v253, v253, v56
	v_add_f32_e32 v253, v253, v57
	v_add_f32_e32 v253, v253, v58
	v_add_f32_e32 v253, v253, v59
	v_add_f32_e32 v253, v253, v60
	v_add_f32_e32 v253, v253, v61
	v_add_f32_e32 v253, v253, v62
	v_add_f32_e32 v253, v253, v63
	v_add_f32_e32 v253, v253, v64
	v_add_f32_e32 v253, v253, v65
	v_add_f32_e32 v253, v253, v66
	v_add_f32_e32 v253, v253, v67
	v_add_f32_e32 v253, v253, v68
	v_add_f32_e32 v253, v253, v69
	v_add_f32_e32 v253, v253, v70
	v_add_f32_e32 v253, v253, v71
	v_add_f32_e32 v253, v253, v72
	v_add_f32_e32 v253, v253, v73
	v_add_f32_e32 v253, v253, v74
	v_add_f32_e32 v253, v253, v75
	v_add_f32_e32 v253, v253, v76
	v_add_f32_e32 v253, v253, v77
	v_add_f32_e32 v253, v253, v78
	v_add_f32_e32 v253, v253, v79
	v_add_f32_e32 v253, v253, v80
	v_add_f32_e32 v253, v253, v81
	ds_bpermute_b32 v252, v9, v253
	s_waitcnt lgkmcnt(0)
	v_add_f32_e32 v253, v253, v252
	ds_bpermute_b32 v252, v10, v253
	s_waitcnt lgkmcnt(0)
; DI void dsa_item(const Params& p, int b, int blk) {
;     ...
;       inv[m] = 1.f / s;
;     }
;     #pragma unroll
;     for (int rd = 0; rd < 4; ++rd)
;       #pragma unroll
;       for (int m = 0; m < 8; ++m) Pb[m * PSTR + rd * 64 + lane] = f2bf(sc[rd][m] * inv[m]);
;     f32x4 oacc[8];
;     #pragma unroll
;     for (int c = 0; c < 8; ++c) oacc[c] = (f32x4){0.f, 0.f, 0.f, 0.f};
;     u32x4 vr[8];
;     {
;       const u32x4 si = *(const u32x4*)(sel + qq * 256 + 8 * g16);
;       #pragma unroll
;       for (int j = 0; j < 8; ++j) {
;         const int ks = 8 * g16 + j;
;         const int idx = ks < cnt ? (int)((si[j >> 1] >> (16 * (j & 1))) & 0xffffu) : 0;
;         vr[j] = ldg<u32x4>(Av + (rowbase + idx) * 128 + n16 * 8);
;       }
;     }
	v_add_f32_e32 v253, v253, v252
	v_div_scale_f32 v2, s[10:11], v253, v253, 1.0
	v_rcp_f32_e32 v3, v2
	s_nop 0
	v_fma_f32 v4, -v2, v3, 1.0
	v_fmac_f32_e32 v3, v4, v3
	v_div_scale_f32 v4, vcc, 1.0, v253, 1.0
	v_mul_f32_e32 v5, v4, v3
	v_fma_f32 v6, -v2, v5, v4
	v_fmac_f32_e32 v5, v6, v3
	v_fma_f32 v4, -v2, v5, v4
	s_nop 0
	v_div_fmas_f32 v4, v4, v3, v5
	v_div_fixup_f32 v4, v4, v253, 1.0
	v_mul_f32_e32 v18, v18, v4
	v_mul_f32_e32 v19, v19, v4
	v_mul_f32_e32 v20, v20, v4
	v_mul_f32_e32 v21, v21, v4
	v_mul_f32_e32 v22, v22, v4
	v_mul_f32_e32 v23, v23, v4
	v_mul_f32_e32 v24, v24, v4
	v_mul_f32_e32 v25, v25, v4
	v_mul_f32_e32 v26, v26, v4
	v_mul_f32_e32 v27, v27, v4
	v_mul_f32_e32 v28, v28, v4
	v_mul_f32_e32 v29, v29, v4
	v_mul_f32_e32 v30, v30, v4
	v_mul_f32_e32 v31, v31, v4
	v_mul_f32_e32 v32, v32, v4
	v_mul_f32_e32 v33, v33, v4
	v_mul_f32_e32 v34, v34, v4
	v_mul_f32_e32 v35, v35, v4
	v_mul_f32_e32 v36, v36, v4
	v_mul_f32_e32 v37, v37, v4
	v_mul_f32_e32 v38, v38, v4
	v_mul_f32_e32 v39, v39, v4
	v_mul_f32_e32 v40, v40, v4
	v_mul_f32_e32 v41, v41, v4
	v_mul_f32_e32 v42, v42, v4
	v_mul_f32_e32 v43, v43, v4
	v_mul_f32_e32 v44, v44, v4
	v_mul_f32_e32 v45, v45, v4
	v_mul_f32_e32 v46, v46, v4
	v_mul_f32_e32 v47, v47, v4
	v_mul_f32_e32 v48, v48, v4
	v_mul_f32_e32 v49, v49, v4
	v_mul_f32_e32 v50, v50, v4
	v_mul_f32_e32 v51, v51, v4
	v_mul_f32_e32 v52, v52, v4
	v_mul_f32_e32 v53, v53, v4
	v_mul_f32_e32 v54, v54, v4
	v_mul_f32_e32 v55, v55, v4
	v_mul_f32_e32 v56, v56, v4
	v_mul_f32_e32 v57, v57, v4
	v_mul_f32_e32 v58, v58, v4
	v_mul_f32_e32 v59, v59, v4
	v_mul_f32_e32 v60, v60, v4
	v_mul_f32_e32 v61, v61, v4
	v_mul_f32_e32 v62, v62, v4
	v_mul_f32_e32 v63, v63, v4
	v_mul_f32_e32 v64, v64, v4
	v_mul_f32_e32 v65, v65, v4
	v_mul_f32_e32 v66, v66, v4
	v_mul_f32_e32 v67, v67, v4
	v_mul_f32_e32 v68, v68, v4
	v_mul_f32_e32 v69, v69, v4
	v_mul_f32_e32 v70, v70, v4
	v_mul_f32_e32 v71, v71, v4
	v_mul_f32_e32 v72, v72, v4
	v_mul_f32_e32 v73, v73, v4
	v_mul_f32_e32 v74, v74, v4
	v_mul_f32_e32 v75, v75, v4
	v_mul_f32_e32 v76, v76, v4
	v_mul_f32_e32 v77, v77, v4
	v_mul_f32_e32 v78, v78, v4
	v_mul_f32_e32 v79, v79, v4
	v_mul_f32_e32 v80, v80, v4
	v_mul_f32_e32 v81, v81, v4
	v_cvt_pk_bf16_f32 v18, v18, v19
	v_cvt_pk_bf16_f32 v19, v20, v21
	v_cvt_pk_bf16_f32 v22, v22, v23
	v_cvt_pk_bf16_f32 v23, v24, v25
	v_cvt_pk_bf16_f32 v26, v26, v27
	v_cvt_pk_bf16_f32 v27, v28, v29
	v_cvt_pk_bf16_f32 v30, v30, v31
	v_cvt_pk_bf16_f32 v31, v32, v33
	v_cvt_pk_bf16_f32 v34, v34, v35
	v_cvt_pk_bf16_f32 v35, v36, v37
	v_cvt_pk_bf16_f32 v38, v38, v39
	v_cvt_pk_bf16_f32 v39, v40, v41
	v_cvt_pk_bf16_f32 v42, v42, v43
	v_cvt_pk_bf16_f32 v43, v44, v45
	v_cvt_pk_bf16_f32 v46, v46, v47
	v_cvt_pk_bf16_f32 v47, v48, v49
	v_cvt_pk_bf16_f32 v50, v50, v51
	v_cvt_pk_bf16_f32 v51, v52, v53
	v_cvt_pk_bf16_f32 v54, v54, v55
	v_cvt_pk_bf16_f32 v55, v56, v57
	v_cvt_pk_bf16_f32 v58, v58, v59
	v_cvt_pk_bf16_f32 v59, v60, v61
	v_cvt_pk_bf16_f32 v62, v62, v63
	v_cvt_pk_bf16_f32 v63, v64, v65
	v_cvt_pk_bf16_f32 v66, v66, v67
	v_cvt_pk_bf16_f32 v67, v68, v69
	v_cvt_pk_bf16_f32 v70, v70, v71
	v_cvt_pk_bf16_f32 v71, v72, v73
	v_cvt_pk_bf16_f32 v74, v74, v75
	v_cvt_pk_bf16_f32 v75, v76, v77
	v_cvt_pk_bf16_f32 v78, v78, v79
	v_cvt_pk_bf16_f32 v79, v80, v81
	s_mov_b32 exec_lo, 0x00ff00ff
	s_mov_b32 exec_hi, 0x00ff00ff
	ds_write_b64 v138, v[18:19]
	ds_write_b64 v138, v[22:23] offset:32
	ds_write_b64 v138, v[26:27] offset:64
	ds_write_b64 v138, v[30:31] offset:96
	ds_write_b64 v138, v[34:35] offset:128
	ds_write_b64 v138, v[38:39] offset:160
	ds_write_b64 v138, v[42:43] offset:192
	ds_write_b64 v138, v[46:47] offset:224
	ds_write_b64 v138, v[50:51] offset:256
	ds_write_b64 v138, v[54:55] offset:288
	ds_write_b64 v138, v[58:59] offset:320
	ds_write_b64 v138, v[62:63] offset:352
	ds_write_b64 v138, v[66:67] offset:384
	ds_write_b64 v138, v[70:71] offset:416
	ds_write_b64 v138, v[74:75] offset:448
	ds_write_b64 v138, v[78:79] offset:480
	s_mov_b64 exec, -1
	v_lshlrev_b64 v[66:67], 9, v[152:153]
	v_mov_b32_e32 v68, v161
	v_mov_b32_e32 v50, 0
	v_mov_b32_e32 v51, 0
	v_mov_b32_e32 v52, 0
	v_mov_b32_e32 v53, 0
	v_mov_b32_e32 v38, 0
	v_mov_b32_e32 v39, 0
	v_mov_b32_e32 v40, 0
	v_mov_b32_e32 v41, 0
	v_mov_b32_e32 v30, 0
	v_mov_b32_e32 v31, 0
	v_mov_b32_e32 v32, 0
	v_mov_b32_e32 v33, 0
	v_mov_b32_e32 v18, 0
	v_mov_b32_e32 v19, 0
	v_mov_b32_e32 v20, 0
	v_mov_b32_e32 v21, 0
	v_mov_b32_e32 v42, 0
	v_mov_b32_e32 v43, 0
	v_mov_b32_e32 v44, 0
	v_mov_b32_e32 v45, 0
	v_mov_b32_e32 v26, 0
	v_mov_b32_e32 v27, 0
	v_mov_b32_e32 v28, 0
	v_mov_b32_e32 v29, 0
	v_mov_b32_e32 v14, 0
	v_mov_b32_e32 v15, 0
	v_mov_b32_e32 v16, 0
	v_mov_b32_e32 v17, 0
	v_mov_b32_e32 v6, 0
	v_mov_b32_e32 v7, 0
	v_mov_b32_e32 v8, 0
	v_mov_b32_e32 v9, 0
	v_and_b32_e32 v253, 15, v187
	v_lshlrev_b32_e32 v253, 4, v253
	ds_read_b128 v[248:251], v242 offset:128
	s_waitcnt lgkmcnt(0)
	s_cmpk_ge_i32 s100, 0x60
	s_cbranch_scc0 .Lgv2_slow
	s_mov_b32 vcc_lo, 0x0c050400
	s_mov_b32 vcc_hi, 0x0c070600
	v_perm_b32 v244, v248, v253, vcc_lo
	global_load_dwordx4 v[2:5], v244, s[12:13]
	v_perm_b32 v245, v248, v253, vcc_hi
	global_load_dwordx4 v[10:13], v245, s[12:13]
	v_perm_b32 v246, v249, v253, vcc_lo
	global_load_dwordx4 v[22:25], v246, s[12:13]
	v_perm_b32 v247, v249, v253, vcc_hi
	global_load_dwordx4 v[34:37], v247, s[12:13]
	v_perm_b32 v244, v250, v253, vcc_lo
	global_load_dwordx4 v[46:49], v244, s[12:13]
	v_perm_b32 v245, v250, v253, vcc_hi
	global_load_dwordx4 v[54:57], v245, s[12:13]
	v_perm_b32 v246, v251, v253, vcc_lo
	global_load_dwordx4 v[58:61], v246, s[12:13]
	v_perm_b32 v247, v251, v253, vcc_hi
	global_load_dwordx4 v[62:65], v247, s[12:13]
	s_branch .Lgv2_done
; DI void dsa_item(const Params& p, int b, int blk) {
;     ...
;     for (int kc = 0; kc < 8; ++kc) {
;       #pragma unroll
;       for (int j = 0; j < 8; ++j) {
;         const unsigned row = 8 * g16 + j;
;         *(u32x4*)(Vc + 256u * row + 16u * ((unsigned)n16 ^ (((row & 3) << 2) | ((row >> 2) & 3)))) = vr[j];
;       }
;       if (kc < 7) {
;         const u32x4 si = *(const u32x4*)(sel + qq * 256 + (kc + 1) * 32 + 8 * g16);
;         #pragma unroll
;         for (int j = 0; j < 8; ++j) {
;           const int ks = (kc + 1) * 32 + 8 * g16 + j;
;           const int idx = ks < cnt ? (int)((si[j >> 1] >> (16 * (j & 1))) & 0xffffu) : 0;
;           vr[j] = ldg<u32x4>(Av + (rowbase + idx) * 128 + n16 * 8);
;         }
;       }
.Lgv2_slow:
	v_add_u32_e32 v243, 0xffffffc0, v206
	v_cmp_lt_i32_e32 vcc, v156, v243
	s_nop 1
	v_cndmask_b32_sdwa v240, v1, v248, vcc dst_sel:DWORD dst_unused:UNUSED_PAD src0_sel:DWORD src1_sel:WORD_0
	v_cmp_lt_i32_e32 vcc, v192, v243
	v_lshl_add_u32 v244, v240, 8, v253
	global_load_dwordx4 v[2:5], v244, s[12:13]
	v_cndmask_b32_sdwa v240, v1, v248, vcc dst_sel:DWORD dst_unused:UNUSED_PAD src0_sel:DWORD src1_sel:WORD_1
	v_cmp_lt_i32_e32 vcc, v193, v243
	v_lshl_add_u32 v245, v240, 8, v253
	global_load_dwordx4 v[10:13], v245, s[12:13]
	v_cndmask_b32_sdwa v240, v1, v249, vcc dst_sel:DWORD dst_unused:UNUSED_PAD src0_sel:DWORD src1_sel:WORD_0
	v_cmp_lt_i32_e32 vcc, v194, v243
	v_lshl_add_u32 v246, v240, 8, v253
	global_load_dwordx4 v[22:25], v246, s[12:13]
	v_cndmask_b32_sdwa v240, v1, v249, vcc dst_sel:DWORD dst_unused:UNUSED_PAD src0_sel:DWORD src1_sel:WORD_1
	v_cmp_lt_i32_e32 vcc, v157, v243
	v_lshl_add_u32 v247, v240, 8, v253
	global_load_dwordx4 v[34:37], v247, s[12:13]
	v_cndmask_b32_sdwa v240, v1, v250, vcc dst_sel:DWORD dst_unused:UNUSED_PAD src0_sel:DWORD src1_sel:WORD_0
	v_cmp_lt_i32_e32 vcc, v195, v243
	v_lshl_add_u32 v244, v240, 8, v253
	global_load_dwordx4 v[46:49], v244, s[12:13]
	v_cndmask_b32_sdwa v240, v1, v250, vcc dst_sel:DWORD dst_unused:UNUSED_PAD src0_sel:DWORD src1_sel:WORD_1
	v_cmp_lt_i32_e32 vcc, v196, v243
	v_lshl_add_u32 v245, v240, 8, v253
	global_load_dwordx4 v[54:57], v245, s[12:13]
	v_cndmask_b32_sdwa v240, v1, v251, vcc dst_sel:DWORD dst_unused:UNUSED_PAD src0_sel:DWORD src1_sel:WORD_0
	v_cmp_lt_i32_e32 vcc, v197, v243
	v_lshl_add_u32 v246, v240, 8, v253
	global_load_dwordx4 v[58:61], v246, s[12:13]
	v_cndmask_b32_sdwa v240, v1, v251, vcc dst_sel:DWORD dst_unused:UNUSED_PAD src0_sel:DWORD src1_sel:WORD_1
	v_lshl_add_u32 v247, v240, 8, v253
	global_load_dwordx4 v[62:65], v247, s[12:13]
.Lgv2_done:
	s_waitcnt vmcnt(16)
	ds_write_b128 v198, v[208:211]
	ds_write_b128 v199, v[212:215]
	ds_write_b128 v200, v[216:219]
	ds_write_b128 v201, v[220:223]
	ds_write_b128 v202, v[224:227]
	ds_write_b128 v203, v[228:231]
	ds_write_b128 v204, v[232:235]
	ds_write_b128 v205, v[236:239]
	ds_read_b128 v[248:251], v242 offset:192
	s_waitcnt lgkmcnt(0)
	s_cmpk_ge_i32 s100, 0x80
	s_cbranch_scc0 .Lgv3_slow
	s_mov_b32 vcc_lo, 0x0c050400
	s_mov_b32 vcc_hi, 0x0c070600
	v_perm_b32 v244, v248, v253, vcc_lo
	global_load_dwordx4 v[208:211], v244, s[12:13]
	v_perm_b32 v245, v248, v253, vcc_hi
	global_load_dwordx4 v[212:215], v245, s[12:13]
	v_perm_b32 v246, v249, v253, vcc_lo
	global_load_dwordx4 v[216:219], v246, s[12:13]
	v_perm_b32 v247, v249, v253, vcc_hi
	global_load_dwordx4 v[220:223], v247, s[12:13]
	v_perm_b32 v244, v250, v253, vcc_lo
	global_load_dwordx4 v[224:227], v244, s[12:13]
	v_perm_b32 v245, v250, v253, vcc_hi
	global_load_dwordx4 v[228:231], v245, s[12:13]
	v_perm_b32 v246, v251, v253, vcc_lo
	global_load_dwordx4 v[232:235], v246, s[12:13]
	v_perm_b32 v247, v251, v253, vcc_hi
	global_load_dwordx4 v[236:239], v247, s[12:13]
	s_branch .Lgv3_done
.Lgv3_slow:
	v_add_u32_e32 v243, 0xffffffa0, v206
	v_cmp_lt_i32_e32 vcc, v156, v243
	s_nop 1
	v_cndmask_b32_sdwa v240, v1, v248, vcc dst_sel:DWORD dst_unused:UNUSED_PAD src0_sel:DWORD src1_sel:WORD_0
	v_cmp_lt_i32_e32 vcc, v192, v243
	v_lshl_add_u32 v244, v240, 8, v253
	global_load_dwordx4 v[208:211], v244, s[12:13]
	v_cndmask_b32_sdwa v240, v1, v248, vcc dst_sel:DWORD dst_unused:UNUSED_PAD src0_sel:DWORD src1_sel:WORD_1
	v_cmp_lt_i32_e32 vcc, v193, v243
	v_lshl_add_u32 v245, v240, 8, v253
	global_load_dwordx4 v[212:215], v245, s[12:13]
	v_cndmask_b32_sdwa v240, v1, v249, vcc dst_sel:DWORD dst_unused:UNUSED_PAD src0_sel:DWORD src1_sel:WORD_0
	v_cmp_lt_i32_e32 vcc, v194, v243
	v_lshl_add_u32 v246, v240, 8, v253
	global_load_dwordx4 v[216:219], v246, s[12:13]
	v_cndmask_b32_sdwa v240, v1, v249, vcc dst_sel:DWORD dst_unused:UNUSED_PAD src0_sel:DWORD src1_sel:WORD_1
	v_cmp_lt_i32_e32 vcc, v157, v243
	v_lshl_add_u32 v247, v240, 8, v253
	global_load_dwordx4 v[220:223], v247, s[12:13]
	v_cndmask_b32_sdwa v240, v1, v250, vcc dst_sel:DWORD dst_unused:UNUSED_PAD src0_sel:DWORD src1_sel:WORD_0
	v_cmp_lt_i32_e32 vcc, v195, v243
	v_lshl_add_u32 v244, v240, 8, v253
	global_load_dwordx4 v[224:227], v244, s[12:13]
	v_cndmask_b32_sdwa v240, v1, v250, vcc dst_sel:DWORD dst_unused:UNUSED_PAD src0_sel:DWORD src1_sel:WORD_1
	v_cmp_lt_i32_e32 vcc, v196, v243
	v_lshl_add_u32 v245, v240, 8, v253
	global_load_dwordx4 v[228:231], v245, s[12:13]
	v_cndmask_b32_sdwa v240, v1, v251, vcc dst_sel:DWORD dst_unused:UNUSED_PAD src0_sel:DWORD src1_sel:WORD_0
	v_cmp_lt_i32_e32 vcc, v197, v243
	v_lshl_add_u32 v246, v240, 8, v253
	global_load_dwordx4 v[232:235], v246, s[12:13]
	v_cndmask_b32_sdwa v240, v1, v251, vcc dst_sel:DWORD dst_unused:UNUSED_PAD src0_sel:DWORD src1_sel:WORD_1
	v_lshl_add_u32 v247, v240, 8, v253
	global_load_dwordx4 v[236:239], v247, s[12:13]
; DI void dsa_item(const Params& p, int b, int blk) {
;     ...
;     for (int kc = 0; kc < 8; ++kc) {
;       #pragma unroll
;       for (int j = 0; j < 8; ++j) {
;         const unsigned row = 8 * g16 + j;
;         *(u32x4*)(Vc + 256u * row + 16u * ((unsigned)n16 ^ (((row & 3) << 2) | ((row >> 2) & 3)))) = vr[j];
;       }
;       if (kc < 7) {
;         const u32x4 si = *(const u32x4*)(sel + qq * 256 + (kc + 1) * 32 + 8 * g16);
;         #pragma unroll
;         for (int j = 0; j < 8; ++j) {
;           const int ks = (kc + 1) * 32 + 8 * g16 + j;
;           const int idx = ks < cnt ? (int)((si[j >> 1] >> (16 * (j & 1))) & 0xffffu) : 0;
;           vr[j] = ldg<u32x4>(Av + (rowbase + idx) * 128 + n16 * 8);
;         }
;       }
;       const bf16x8 pa = *(const bf16x8*)(Pb + arow * PSTR + kc * 32 + g16 * 8);
;       u32x2 t0[8], t1[8];
;       asm volatile(
;           "s_waitcnt lgkmcnt(0)\n\t"
;           "ds_read_b64_tr_b16 %0, %16\n\tds_read_b64_tr_b16 %1, %17\n\tds_read_b64_tr_b16 %2, %18\n\tds_read_b64_tr_b16 %3, %19\n\t"
;           "ds_read_b64_tr_b16 %4, %20\n\tds_read_b64_tr_b16 %5, %21\n\tds_read_b64_tr_b16 %6, %22\n\tds_read_b64_tr_b16 %7, %23\n\t"
;           "ds_read_b64_tr_b16 %8, %24\n\tds_read_b64_tr_b16 %9, %25\n\tds_read_b64_tr_b16 %10, %26\n\tds_read_b64_tr_b16 %11, %27\n\t"
;           "ds_read_b64_tr_b16 %12, %28\n\tds_read_b64_tr_b16 %13, %29\n\tds_read_b64_tr_b16 %14, %30\n\tds_read_b64_tr_b16 %15, %31\n\t"
;           "s_waitcnt lgkmcnt(0)"
;           : "=&v"(t0[0]), "=&v"(t1[0]), "=&v"(t0[1]), "=&v"(t1[1]), "=&v"(t0[2]), "=&v"(t1[2]), "=&v"(t0[3]), "=&v"(t1[3]),
;             "=&v"(t0[4]), "=&v"(t1[4]), "=&v"(t0[5]), "=&v"(t1[5]), "=&v"(t0[6]), "=&v"(t1[6]), "=&v"(t0[7]), "=&v"(t1[7])
;           : "v"(lds_base + taddr[0][0]), "v"(lds_base + taddr[0][1]), "v"(lds_base + taddr[1][0]), "v"(lds_base + taddr[1][1]),
;             "v"(lds_base + taddr[2][0]), "v"(lds_base + taddr[2][1]), "v"(lds_base + taddr[3][0]), "v"(lds_base + taddr[3][1]),
;             "v"(lds_base + taddr[4][0]), "v"(lds_base + taddr[4][1]), "v"(lds_base + taddr[5][0]), "v"(lds_base + taddr[5][1]),
;             "v"(lds_base + taddr[6][0]), "v"(lds_base + taddr[6][1]), "v"(lds_base + taddr[7][0]), "v"(lds_base + taddr[7][1])
;           : "memory");
;       #pragma unroll
;       for (int c = 0; c < 8; ++c) {
.Lgv3_done:
	ds_read_b128 v[70:73], v68
	s_waitcnt lgkmcnt(0)
	ds_read_b64_tr_b16 v[102:103], v162
	ds_read_b64_tr_b16 v[104:105], v163
	ds_read_b64_tr_b16 v[98:99], v164
	ds_read_b64_tr_b16 v[100:101], v165
	ds_read_b64_tr_b16 v[94:95], v166
	ds_read_b64_tr_b16 v[96:97], v167
	ds_read_b64_tr_b16 v[90:91], v168
	ds_read_b64_tr_b16 v[92:93], v169
	ds_read_b64_tr_b16 v[86:87], v170
	ds_read_b64_tr_b16 v[88:89], v171
	ds_read_b64_tr_b16 v[82:83], v172
	ds_read_b64_tr_b16 v[84:85], v173
	ds_read_b64_tr_b16 v[78:79], v174
	ds_read_b64_tr_b16 v[80:81], v175
	ds_read_b64_tr_b16 v[74:75], v176
	ds_read_b64_tr_b16 v[76:77], v177
	s_waitcnt lgkmcnt(0)
	v_mfma_f32_16x16x32_bf16 v[50:53], v[70:73], v[102:105], v[50:53]
	v_mfma_f32_16x16x32_bf16 v[38:41], v[70:73], v[98:101], v[38:41]
	v_mfma_f32_16x16x32_bf16 v[30:33], v[70:73], v[94:97], v[30:33]
	v_mfma_f32_16x16x32_bf16 v[18:21], v[70:73], v[90:93], v[18:21]
	v_mfma_f32_16x16x32_bf16 v[42:45], v[70:73], v[86:89], v[42:45]
	v_mfma_f32_16x16x32_bf16 v[26:29], v[70:73], v[82:85], v[26:29]
	v_mfma_f32_16x16x32_bf16 v[14:17], v[70:73], v[78:81], v[14:17]
	v_mfma_f32_16x16x32_bf16 v[6:9], v[70:73], v[74:77], v[6:9]
	s_waitcnt vmcnt(16)
	ds_write_b128 v198, v[106:109]
	ds_write_b128 v199, v[110:113]
	ds_write_b128 v200, v[114:117]
	ds_write_b128 v201, v[118:121]
	ds_write_b128 v202, v[122:125]
	ds_write_b128 v203, v[126:129]
	ds_write_b128 v204, v[130:133]
	ds_write_b128 v205, v[134:137]
	ds_read_b128 v[248:251], v242 offset:256
	s_waitcnt lgkmcnt(0)
	s_cmpk_ge_i32 s100, 0xa0
	s_cbranch_scc0 .Lgv4_slow
	s_mov_b32 vcc_lo, 0x0c050400
	s_mov_b32 vcc_hi, 0x0c070600
	v_perm_b32 v244, v248, v253, vcc_lo
	global_load_dwordx4 v[106:109], v244, s[12:13]
	v_perm_b32 v245, v248, v253, vcc_hi
	global_load_dwordx4 v[110:113], v245, s[12:13]
	v_perm_b32 v246, v249, v253, vcc_lo
	global_load_dwordx4 v[114:117], v246, s[12:13]
	v_perm_b32 v247, v249, v253, vcc_hi
	global_load_dwordx4 v[118:121], v247, s[12:13]
	v_perm_b32 v244, v250, v253, vcc_lo
	global_load_dwordx4 v[122:125], v244, s[12:13]
	v_perm_b32 v245, v250, v253, vcc_hi
	global_load_dwordx4 v[126:129], v245, s[12:13]
	v_perm_b32 v246, v251, v253, vcc_lo
	global_load_dwordx4 v[130:133], v246, s[12:13]
	v_perm_b32 v247, v251, v253, vcc_hi
	global_load_dwordx4 v[134:137], v247, s[12:13]
	s_branch .Lgv4_done
.Lgv4_slow:
	v_add_u32_e32 v243, 0xffffff80, v206
	v_cmp_lt_i32_e32 vcc, v156, v243
	s_nop 1
	v_cndmask_b32_sdwa v240, v1, v248, vcc dst_sel:DWORD dst_unused:UNUSED_PAD src0_sel:DWORD src1_sel:WORD_0
	v_cmp_lt_i32_e32 vcc, v192, v243
	v_lshl_add_u32 v244, v240, 8, v253
	global_load_dwordx4 v[106:109], v244, s[12:13]
	v_cndmask_b32_sdwa v240, v1, v248, vcc dst_sel:DWORD dst_unused:UNUSED_PAD src0_sel:DWORD src1_sel:WORD_1
	v_cmp_lt_i32_e32 vcc, v193, v243
	v_lshl_add_u32 v245, v240, 8, v253
	global_load_dwordx4 v[110:113], v245, s[12:13]
	v_cndmask_b32_sdwa v240, v1, v249, vcc dst_sel:DWORD dst_unused:UNUSED_PAD src0_sel:DWORD src1_sel:WORD_0
	v_cmp_lt_i32_e32 vcc, v194, v243
	v_lshl_add_u32 v246, v240, 8, v253
	global_load_dwordx4 v[114:117], v246, s[12:13]
	v_cndmask_b32_sdwa v240, v1, v249, vcc dst_sel:DWORD dst_unused:UNUSED_PAD src0_sel:DWORD src1_sel:WORD_1
	v_cmp_lt_i32_e32 vcc, v157, v243
	v_lshl_add_u32 v247, v240, 8, v253
	global_load_dwordx4 v[118:121], v247, s[12:13]
	v_cndmask_b32_sdwa v240, v1, v250, vcc dst_sel:DWORD dst_unused:UNUSED_PAD src0_sel:DWORD src1_sel:WORD_0
	v_cmp_lt_i32_e32 vcc, v195, v243
	v_lshl_add_u32 v244, v240, 8, v253
	global_load_dwordx4 v[122:125], v244, s[12:13]
	v_cndmask_b32_sdwa v240, v1, v250, vcc dst_sel:DWORD dst_unused:UNUSED_PAD src0_sel:DWORD src1_sel:WORD_1
	v_cmp_lt_i32_e32 vcc, v196, v243
	v_lshl_add_u32 v245, v240, 8, v253
	global_load_dwordx4 v[126:129], v245, s[12:13]
	v_cndmask_b32_sdwa v240, v1, v251, vcc dst_sel:DWORD dst_unused:UNUSED_PAD src0_sel:DWORD src1_sel:WORD_0
	v_cmp_lt_i32_e32 vcc, v197, v243
	v_lshl_add_u32 v246, v240, 8, v253
	global_load_dwordx4 v[130:133], v246, s[12:13]
	v_cndmask_b32_sdwa v240, v1, v251, vcc dst_sel:DWORD dst_unused:UNUSED_PAD src0_sel:DWORD src1_sel:WORD_1
	v_lshl_add_u32 v247, v240, 8, v253
	global_load_dwordx4 v[134:137], v247, s[12:13]
.Lgv4_done:
	ds_read_b128 v[70:73], v68 offset:64
	s_waitcnt lgkmcnt(0)
	ds_read_b64_tr_b16 v[102:103], v162
	ds_read_b64_tr_b16 v[104:105], v163
	ds_read_b64_tr_b16 v[98:99], v164
	ds_read_b64_tr_b16 v[100:101], v165
	ds_read_b64_tr_b16 v[94:95], v166
	ds_read_b64_tr_b16 v[96:97], v167
	ds_read_b64_tr_b16 v[90:91], v168
	ds_read_b64_tr_b16 v[92:93], v169
	ds_read_b64_tr_b16 v[86:87], v170
	ds_read_b64_tr_b16 v[88:89], v171
	ds_read_b64_tr_b16 v[82:83], v172
	ds_read_b64_tr_b16 v[84:85], v173
	ds_read_b64_tr_b16 v[78:79], v174
	ds_read_b64_tr_b16 v[80:81], v175
	ds_read_b64_tr_b16 v[74:75], v176
	ds_read_b64_tr_b16 v[76:77], v177
	s_waitcnt lgkmcnt(0)
	v_mfma_f32_16x16x32_bf16 v[50:53], v[70:73], v[102:105], v[50:53]
	v_mfma_f32_16x16x32_bf16 v[38:41], v[70:73], v[98:101], v[38:41]
	v_mfma_f32_16x16x32_bf16 v[30:33], v[70:73], v[94:97], v[30:33]
	v_mfma_f32_16x16x32_bf16 v[18:21], v[70:73], v[90:93], v[18:21]
	v_mfma_f32_16x16x32_bf16 v[42:45], v[70:73], v[86:89], v[42:45]
	v_mfma_f32_16x16x32_bf16 v[26:29], v[70:73], v[82:85], v[26:29]
	v_mfma_f32_16x16x32_bf16 v[14:17], v[70:73], v[78:81], v[14:17]
	v_mfma_f32_16x16x32_bf16 v[6:9], v[70:73], v[74:77], v[6:9]
	s_waitcnt vmcnt(16)
	ds_write_b128 v198, v[2:5]
	ds_write_b128 v199, v[10:13]
	ds_write_b128 v200, v[22:25]
	ds_write_b128 v201, v[34:37]
	ds_write_b128 v202, v[46:49]
	ds_write_b128 v203, v[54:57]
	ds_write_b128 v204, v[58:61]
	ds_write_b128 v205, v[62:65]
	ds_read_b128 v[248:251], v242 offset:320
	s_waitcnt lgkmcnt(0)
	s_cmpk_ge_i32 s100, 0xc0
	s_cbranch_scc0 .Lgv5_slow
	s_mov_b32 vcc_lo, 0x0c050400
	s_mov_b32 vcc_hi, 0x0c070600
	v_perm_b32 v244, v248, v253, vcc_lo
	global_load_dwordx4 v[2:5], v244, s[12:13]
	v_perm_b32 v245, v248, v253, vcc_hi
	global_load_dwordx4 v[10:13], v245, s[12:13]
	v_perm_b32 v246, v249, v253, vcc_lo
	global_load_dwordx4 v[22:25], v246, s[12:13]
	v_perm_b32 v247, v249, v253, vcc_hi
	global_load_dwordx4 v[34:37], v247, s[12:13]
	v_perm_b32 v244, v250, v253, vcc_lo
	global_load_dwordx4 v[46:49], v244, s[12:13]
	v_perm_b32 v245, v250, v253, vcc_hi
	global_load_dwordx4 v[54:57], v245, s[12:13]
	v_perm_b32 v246, v251, v253, vcc_lo
	global_load_dwordx4 v[58:61], v246, s[12:13]
	v_perm_b32 v247, v251, v253, vcc_hi
	global_load_dwordx4 v[62:65], v247, s[12:13]
	s_branch .Lgv5_done
; DI void dsa_item(const Params& p, int b, int blk) {
;     ...
;     for (int kc = 0; kc < 8; ++kc) {
;       #pragma unroll
;       for (int j = 0; j < 8; ++j) {
;         const unsigned row = 8 * g16 + j;
;         *(u32x4*)(Vc + 256u * row + 16u * ((unsigned)n16 ^ (((row & 3) << 2) | ((row >> 2) & 3)))) = vr[j];
;       }
;       if (kc < 7) {
;         const u32x4 si = *(const u32x4*)(sel + qq * 256 + (kc + 1) * 32 + 8 * g16);
;         #pragma unroll
;         for (int j = 0; j < 8; ++j) {
;           const int ks = (kc + 1) * 32 + 8 * g16 + j;
;           const int idx = ks < cnt ? (int)((si[j >> 1] >> (16 * (j & 1))) & 0xffffu) : 0;
;           vr[j] = ldg<u32x4>(Av + (rowbase + idx) * 128 + n16 * 8);
;         }
;       }
;       const bf16x8 pa = *(const bf16x8*)(Pb + arow * PSTR + kc * 32 + g16 * 8);
;       u32x2 t0[8], t1[8];
;       asm volatile(
;           "s_waitcnt lgkmcnt(0)\n\t"
;           "ds_read_b64_tr_b16 %0, %16\n\tds_read_b64_tr_b16 %1, %17\n\tds_read_b64_tr_b16 %2, %18\n\tds_read_b64_tr_b16 %3, %19\n\t"
;           "ds_read_b64_tr_b16 %4, %20\n\tds_read_b64_tr_b16 %5, %21\n\tds_read_b64_tr_b16 %6, %22\n\tds_read_b64_tr_b16 %7, %23\n\t"
;           "ds_read_b64_tr_b16 %8, %24\n\tds_read_b64_tr_b16 %9, %25\n\tds_read_b64_tr_b16 %10, %26\n\tds_read_b64_tr_b16 %11, %27\n\t"
;           "ds_read_b64_tr_b16 %12, %28\n\tds_read_b64_tr_b16 %13, %29\n\tds_read_b64_tr_b16 %14, %30\n\tds_read_b64_tr_b16 %15, %31\n\t"
;           "s_waitcnt lgkmcnt(0)"
;           : "=&v"(t0[0]), "=&v"(t1[0]), "=&v"(t0[1]), "=&v"(t1[1]), "=&v"(t0[2]), "=&v"(t1[2]), "=&v"(t0[3]), "=&v"(t1[3]),
;             "=&v"(t0[4]), "=&v"(t1[4]), "=&v"(t0[5]), "=&v"(t1[5]), "=&v"(t0[6]), "=&v"(t1[6]), "=&v"(t0[7]), "=&v"(t1[7])
;           : "v"(lds_base + taddr[0][0]), "v"(lds_base + taddr[0][1]), "v"(lds_base + taddr[1][0]), "v"(lds_base + taddr[1][1]),
;             "v"(lds_base + taddr[2][0]), "v"(lds_base + taddr[2][1]), "v"(lds_base + taddr[3][0]), "v"(lds_base + taddr[3][1]),
;             "v"(lds_base + taddr[4][0]), "v"(lds_base + taddr[4][1]), "v"(lds_base + taddr[5][0]), "v"(lds_base + taddr[5][1]),
;             "v"(lds_base + taddr[6][0]), "v"(lds_base + taddr[6][1]), "v"(lds_base + taddr[7][0]), "v"(lds_base + taddr[7][1])
;           : "memory");
;       #pragma unroll
;       for (int c = 0; c < 8; ++c) {
.Lgv5_slow:
	v_add_u32_e32 v243, 0xffffff60, v206
	v_cmp_lt_i32_e32 vcc, v156, v243
	s_nop 1
	v_cndmask_b32_sdwa v240, v1, v248, vcc dst_sel:DWORD dst_unused:UNUSED_PAD src0_sel:DWORD src1_sel:WORD_0
	v_cmp_lt_i32_e32 vcc, v192, v243
	v_lshl_add_u32 v244, v240, 8, v253
	global_load_dwordx4 v[2:5], v244, s[12:13]
	v_cndmask_b32_sdwa v240, v1, v248, vcc dst_sel:DWORD dst_unused:UNUSED_PAD src0_sel:DWORD src1_sel:WORD_1
	v_cmp_lt_i32_e32 vcc, v193, v243
	v_lshl_add_u32 v245, v240, 8, v253
	global_load_dwordx4 v[10:13], v245, s[12:13]
	v_cndmask_b32_sdwa v240, v1, v249, vcc dst_sel:DWORD dst_unused:UNUSED_PAD src0_sel:DWORD src1_sel:WORD_0
	v_cmp_lt_i32_e32 vcc, v194, v243
	v_lshl_add_u32 v246, v240, 8, v253
	global_load_dwordx4 v[22:25], v246, s[12:13]
	v_cndmask_b32_sdwa v240, v1, v249, vcc dst_sel:DWORD dst_unused:UNUSED_PAD src0_sel:DWORD src1_sel:WORD_1
	v_cmp_lt_i32_e32 vcc, v157, v243
	v_lshl_add_u32 v247, v240, 8, v253
	global_load_dwordx4 v[34:37], v247, s[12:13]
	v_cndmask_b32_sdwa v240, v1, v250, vcc dst_sel:DWORD dst_unused:UNUSED_PAD src0_sel:DWORD src1_sel:WORD_0
	v_cmp_lt_i32_e32 vcc, v195, v243
	v_lshl_add_u32 v244, v240, 8, v253
	global_load_dwordx4 v[46:49], v244, s[12:13]
	v_cndmask_b32_sdwa v240, v1, v250, vcc dst_sel:DWORD dst_unused:UNUSED_PAD src0_sel:DWORD src1_sel:WORD_1
	v_cmp_lt_i32_e32 vcc, v196, v243
	v_lshl_add_u32 v245, v240, 8, v253
	global_load_dwordx4 v[54:57], v245, s[12:13]
	v_cndmask_b32_sdwa v240, v1, v251, vcc dst_sel:DWORD dst_unused:UNUSED_PAD src0_sel:DWORD src1_sel:WORD_0
	v_cmp_lt_i32_e32 vcc, v197, v243
	v_lshl_add_u32 v246, v240, 8, v253
	global_load_dwordx4 v[58:61], v246, s[12:13]
	v_cndmask_b32_sdwa v240, v1, v251, vcc dst_sel:DWORD dst_unused:UNUSED_PAD src0_sel:DWORD src1_sel:WORD_1
	v_lshl_add_u32 v247, v240, 8, v253
	global_load_dwordx4 v[62:65], v247, s[12:13]
.Lgv5_done:
	ds_read_b128 v[70:73], v68 offset:128
	s_waitcnt lgkmcnt(0)
	ds_read_b64_tr_b16 v[102:103], v162
	ds_read_b64_tr_b16 v[104:105], v163
	ds_read_b64_tr_b16 v[98:99], v164
	ds_read_b64_tr_b16 v[100:101], v165
	ds_read_b64_tr_b16 v[94:95], v166
	ds_read_b64_tr_b16 v[96:97], v167
	ds_read_b64_tr_b16 v[90:91], v168
	ds_read_b64_tr_b16 v[92:93], v169
	ds_read_b64_tr_b16 v[86:87], v170
	ds_read_b64_tr_b16 v[88:89], v171
	ds_read_b64_tr_b16 v[82:83], v172
	ds_read_b64_tr_b16 v[84:85], v173
	ds_read_b64_tr_b16 v[78:79], v174
	ds_read_b64_tr_b16 v[80:81], v175
	ds_read_b64_tr_b16 v[74:75], v176
	ds_read_b64_tr_b16 v[76:77], v177
	s_waitcnt lgkmcnt(0)
	v_mfma_f32_16x16x32_bf16 v[50:53], v[70:73], v[102:105], v[50:53]
	v_mfma_f32_16x16x32_bf16 v[38:41], v[70:73], v[98:101], v[38:41]
	v_mfma_f32_16x16x32_bf16 v[30:33], v[70:73], v[94:97], v[30:33]
	v_mfma_f32_16x16x32_bf16 v[18:21], v[70:73], v[90:93], v[18:21]
	v_mfma_f32_16x16x32_bf16 v[42:45], v[70:73], v[86:89], v[42:45]
	v_mfma_f32_16x16x32_bf16 v[26:29], v[70:73], v[82:85], v[26:29]
	v_mfma_f32_16x16x32_bf16 v[14:17], v[70:73], v[78:81], v[14:17]
	v_mfma_f32_16x16x32_bf16 v[6:9], v[70:73], v[74:77], v[6:9]
	s_waitcnt vmcnt(16)
	ds_write_b128 v198, v[208:211]
	ds_write_b128 v199, v[212:215]
	ds_write_b128 v200, v[216:219]
	ds_write_b128 v201, v[220:223]
	ds_write_b128 v202, v[224:227]
	ds_write_b128 v203, v[228:231]
	ds_write_b128 v204, v[232:235]
	ds_write_b128 v205, v[236:239]
	ds_read_b128 v[248:251], v242 offset:384
	s_waitcnt lgkmcnt(0)
	s_cmpk_ge_i32 s100, 0xe0
	s_cbranch_scc0 .Lgv6_slow
	s_mov_b32 vcc_lo, 0x0c050400
	s_mov_b32 vcc_hi, 0x0c070600
	v_perm_b32 v244, v248, v253, vcc_lo
	global_load_dwordx4 v[208:211], v244, s[12:13]
	v_perm_b32 v245, v248, v253, vcc_hi
	global_load_dwordx4 v[212:215], v245, s[12:13]
	v_perm_b32 v246, v249, v253, vcc_lo
	global_load_dwordx4 v[216:219], v246, s[12:13]
	v_perm_b32 v247, v249, v253, vcc_hi
	global_load_dwordx4 v[220:223], v247, s[12:13]
	v_perm_b32 v244, v250, v253, vcc_lo
	global_load_dwordx4 v[224:227], v244, s[12:13]
	v_perm_b32 v245, v250, v253, vcc_hi
	global_load_dwordx4 v[228:231], v245, s[12:13]
	v_perm_b32 v246, v251, v253, vcc_lo
	global_load_dwordx4 v[232:235], v246, s[12:13]
	v_perm_b32 v247, v251, v253, vcc_hi
	global_load_dwordx4 v[236:239], v247, s[12:13]
	s_branch .Lgv6_done
.Lgv6_slow:
	v_add_u32_e32 v243, 0xffffff40, v206
	v_cmp_lt_i32_e32 vcc, v156, v243
	s_nop 1
	v_cndmask_b32_sdwa v240, v1, v248, vcc dst_sel:DWORD dst_unused:UNUSED_PAD src0_sel:DWORD src1_sel:WORD_0
	v_cmp_lt_i32_e32 vcc, v192, v243
	v_lshl_add_u32 v244, v240, 8, v253
	global_load_dwordx4 v[208:211], v244, s[12:13]
	v_cndmask_b32_sdwa v240, v1, v248, vcc dst_sel:DWORD dst_unused:UNUSED_PAD src0_sel:DWORD src1_sel:WORD_1
	v_cmp_lt_i32_e32 vcc, v193, v243
	v_lshl_add_u32 v245, v240, 8, v253
	global_load_dwordx4 v[212:215], v245, s[12:13]
	v_cndmask_b32_sdwa v240, v1, v249, vcc dst_sel:DWORD dst_unused:UNUSED_PAD src0_sel:DWORD src1_sel:WORD_0
	v_cmp_lt_i32_e32 vcc, v194, v243
	v_lshl_add_u32 v246, v240, 8, v253
	global_load_dwordx4 v[216:219], v246, s[12:13]
	v_cndmask_b32_sdwa v240, v1, v249, vcc dst_sel:DWORD dst_unused:UNUSED_PAD src0_sel:DWORD src1_sel:WORD_1
	v_cmp_lt_i32_e32 vcc, v157, v243
	v_lshl_add_u32 v247, v240, 8, v253
	global_load_dwordx4 v[220:223], v247, s[12:13]
	v_cndmask_b32_sdwa v240, v1, v250, vcc dst_sel:DWORD dst_unused:UNUSED_PAD src0_sel:DWORD src1_sel:WORD_0
	v_cmp_lt_i32_e32 vcc, v195, v243
	v_lshl_add_u32 v244, v240, 8, v253
	global_load_dwordx4 v[224:227], v244, s[12:13]
	v_cndmask_b32_sdwa v240, v1, v250, vcc dst_sel:DWORD dst_unused:UNUSED_PAD src0_sel:DWORD src1_sel:WORD_1
	v_cmp_lt_i32_e32 vcc, v196, v243
	v_lshl_add_u32 v245, v240, 8, v253
	global_load_dwordx4 v[228:231], v245, s[12:13]
	v_cndmask_b32_sdwa v240, v1, v251, vcc dst_sel:DWORD dst_unused:UNUSED_PAD src0_sel:DWORD src1_sel:WORD_0
	v_cmp_lt_i32_e32 vcc, v197, v243
	v_lshl_add_u32 v246, v240, 8, v253
	global_load_dwordx4 v[232:235], v246, s[12:13]
	v_cndmask_b32_sdwa v240, v1, v251, vcc dst_sel:DWORD dst_unused:UNUSED_PAD src0_sel:DWORD src1_sel:WORD_1
	v_lshl_add_u32 v247, v240, 8, v253
	global_load_dwordx4 v[236:239], v247, s[12:13]
; DI void dsa_item(const Params& p, int b, int blk) {
;     ...
;     for (int kc = 0; kc < 8; ++kc) {
;       #pragma unroll
;       for (int j = 0; j < 8; ++j) {
;         const unsigned row = 8 * g16 + j;
;         *(u32x4*)(Vc + 256u * row + 16u * ((unsigned)n16 ^ (((row & 3) << 2) | ((row >> 2) & 3)))) = vr[j];
;       }
;       if (kc < 7) {
;         const u32x4 si = *(const u32x4*)(sel + qq * 256 + (kc + 1) * 32 + 8 * g16);
;         #pragma unroll
;         for (int j = 0; j < 8; ++j) {
;           const int ks = (kc + 1) * 32 + 8 * g16 + j;
;           const int idx = ks < cnt ? (int)((si[j >> 1] >> (16 * (j & 1))) & 0xffffu) : 0;
;           vr[j] = ldg<u32x4>(Av + (rowbase + idx) * 128 + n16 * 8);
;         }
;       }
;       const bf16x8 pa = *(const bf16x8*)(Pb + arow * PSTR + kc * 32 + g16 * 8);
;       u32x2 t0[8], t1[8];
;       asm volatile(
;           "s_waitcnt lgkmcnt(0)\n\t"
;           "ds_read_b64_tr_b16 %0, %16\n\tds_read_b64_tr_b16 %1, %17\n\tds_read_b64_tr_b16 %2, %18\n\tds_read_b64_tr_b16 %3, %19\n\t"
;           "ds_read_b64_tr_b16 %4, %20\n\tds_read_b64_tr_b16 %5, %21\n\tds_read_b64_tr_b16 %6, %22\n\tds_read_b64_tr_b16 %7, %23\n\t"
;           "ds_read_b64_tr_b16 %8, %24\n\tds_read_b64_tr_b16 %9, %25\n\tds_read_b64_tr_b16 %10, %26\n\tds_read_b64_tr_b16 %11, %27\n\t"
;           "ds_read_b64_tr_b16 %12, %28\n\tds_read_b64_tr_b16 %13, %29\n\tds_read_b64_tr_b16 %14, %30\n\tds_read_b64_tr_b16 %15, %31\n\t"
;           "s_waitcnt lgkmcnt(0)"
;           : "=&v"(t0[0]), "=&v"(t1[0]), "=&v"(t0[1]), "=&v"(t1[1]), "=&v"(t0[2]), "=&v"(t1[2]), "=&v"(t0[3]), "=&v"(t1[3]),
;             "=&v"(t0[4]), "=&v"(t1[4]), "=&v"(t0[5]), "=&v"(t1[5]), "=&v"(t0[6]), "=&v"(t1[6]), "=&v"(t0[7]), "=&v"(t1[7])
;           : "v"(lds_base + taddr[0][0]), "v"(lds_base + taddr[0][1]), "v"(lds_base + taddr[1][0]), "v"(lds_base + taddr[1][1]),
;             "v"(lds_base + taddr[2][0]), "v"(lds_base + taddr[2][1]), "v"(lds_base + taddr[3][0]), "v"(lds_base + taddr[3][1]),
;             "v"(lds_base + taddr[4][0]), "v"(lds_base + taddr[4][1]), "v"(lds_base + taddr[5][0]), "v"(lds_base + taddr[5][1]),
;             "v"(lds_base + taddr[6][0]), "v"(lds_base + taddr[6][1]), "v"(lds_base + taddr[7][0]), "v"(lds_base + taddr[7][1])
;           : "memory");
;       #pragma unroll
;       for (int c = 0; c < 8; ++c) {
.Lgv6_done:
	ds_read_b128 v[70:73], v68 offset:192
	s_waitcnt lgkmcnt(0)
	ds_read_b64_tr_b16 v[102:103], v162
	ds_read_b64_tr_b16 v[104:105], v163
	ds_read_b64_tr_b16 v[98:99], v164
	ds_read_b64_tr_b16 v[100:101], v165
	ds_read_b64_tr_b16 v[94:95], v166
	ds_read_b64_tr_b16 v[96:97], v167
	ds_read_b64_tr_b16 v[90:91], v168
	ds_read_b64_tr_b16 v[92:93], v169
	ds_read_b64_tr_b16 v[86:87], v170
	ds_read_b64_tr_b16 v[88:89], v171
	ds_read_b64_tr_b16 v[82:83], v172
	ds_read_b64_tr_b16 v[84:85], v173
	ds_read_b64_tr_b16 v[78:79], v174
	ds_read_b64_tr_b16 v[80:81], v175
	ds_read_b64_tr_b16 v[74:75], v176
	ds_read_b64_tr_b16 v[76:77], v177
	s_waitcnt lgkmcnt(0)
	v_mfma_f32_16x16x32_bf16 v[50:53], v[70:73], v[102:105], v[50:53]
	v_mfma_f32_16x16x32_bf16 v[38:41], v[70:73], v[98:101], v[38:41]
	v_mfma_f32_16x16x32_bf16 v[30:33], v[70:73], v[94:97], v[30:33]
	v_mfma_f32_16x16x32_bf16 v[18:21], v[70:73], v[90:93], v[18:21]
	v_mfma_f32_16x16x32_bf16 v[42:45], v[70:73], v[86:89], v[42:45]
	v_mfma_f32_16x16x32_bf16 v[26:29], v[70:73], v[82:85], v[26:29]
	v_mfma_f32_16x16x32_bf16 v[14:17], v[70:73], v[78:81], v[14:17]
	v_mfma_f32_16x16x32_bf16 v[6:9], v[70:73], v[74:77], v[6:9]
	s_waitcnt vmcnt(16)
	ds_write_b128 v198, v[106:109]
	ds_write_b128 v199, v[110:113]
	ds_write_b128 v200, v[114:117]
	ds_write_b128 v201, v[118:121]
	ds_write_b128 v202, v[122:125]
	ds_write_b128 v203, v[126:129]
	ds_write_b128 v204, v[130:133]
	ds_write_b128 v205, v[134:137]
	ds_read_b128 v[248:251], v242 offset:448
	s_waitcnt lgkmcnt(0)
	s_cmpk_ge_i32 s100, 0x100
	s_cbranch_scc0 .Lgv7_slow
	s_mov_b32 vcc_lo, 0x0c050400
	s_mov_b32 vcc_hi, 0x0c070600
	v_perm_b32 v244, v248, v253, vcc_lo
	global_load_dwordx4 v[106:109], v244, s[12:13]
	v_perm_b32 v245, v248, v253, vcc_hi
	global_load_dwordx4 v[110:113], v245, s[12:13]
	v_perm_b32 v246, v249, v253, vcc_lo
	global_load_dwordx4 v[114:117], v246, s[12:13]
	v_perm_b32 v247, v249, v253, vcc_hi
	global_load_dwordx4 v[118:121], v247, s[12:13]
	v_perm_b32 v244, v250, v253, vcc_lo
	global_load_dwordx4 v[122:125], v244, s[12:13]
	v_perm_b32 v245, v250, v253, vcc_hi
	global_load_dwordx4 v[126:129], v245, s[12:13]
	v_perm_b32 v246, v251, v253, vcc_lo
	global_load_dwordx4 v[130:133], v246, s[12:13]
	v_perm_b32 v247, v251, v253, vcc_hi
	global_load_dwordx4 v[134:137], v247, s[12:13]
	s_branch .Lgv7_done
.Lgv7_slow:
	v_add_u32_e32 v243, 0xffffff20, v206
	v_cmp_lt_i32_e32 vcc, v156, v243
	s_nop 1
	v_cndmask_b32_sdwa v240, v1, v248, vcc dst_sel:DWORD dst_unused:UNUSED_PAD src0_sel:DWORD src1_sel:WORD_0
	v_cmp_lt_i32_e32 vcc, v192, v243
	v_lshl_add_u32 v244, v240, 8, v253
	global_load_dwordx4 v[106:109], v244, s[12:13]
	v_cndmask_b32_sdwa v240, v1, v248, vcc dst_sel:DWORD dst_unused:UNUSED_PAD src0_sel:DWORD src1_sel:WORD_1
	v_cmp_lt_i32_e32 vcc, v193, v243
	v_lshl_add_u32 v245, v240, 8, v253
	global_load_dwordx4 v[110:113], v245, s[12:13]
	v_cndmask_b32_sdwa v240, v1, v249, vcc dst_sel:DWORD dst_unused:UNUSED_PAD src0_sel:DWORD src1_sel:WORD_0
	v_cmp_lt_i32_e32 vcc, v194, v243
	v_lshl_add_u32 v246, v240, 8, v253
	global_load_dwordx4 v[114:117], v246, s[12:13]
	v_cndmask_b32_sdwa v240, v1, v249, vcc dst_sel:DWORD dst_unused:UNUSED_PAD src0_sel:DWORD src1_sel:WORD_1
	v_cmp_lt_i32_e32 vcc, v157, v243
	v_lshl_add_u32 v247, v240, 8, v253
	global_load_dwordx4 v[118:121], v247, s[12:13]
	v_cndmask_b32_sdwa v240, v1, v250, vcc dst_sel:DWORD dst_unused:UNUSED_PAD src0_sel:DWORD src1_sel:WORD_0
	v_cmp_lt_i32_e32 vcc, v195, v243
	v_lshl_add_u32 v244, v240, 8, v253
	global_load_dwordx4 v[122:125], v244, s[12:13]
	v_cndmask_b32_sdwa v240, v1, v250, vcc dst_sel:DWORD dst_unused:UNUSED_PAD src0_sel:DWORD src1_sel:WORD_1
	v_cmp_lt_i32_e32 vcc, v196, v243
	v_lshl_add_u32 v245, v240, 8, v253
	global_load_dwordx4 v[126:129], v245, s[12:13]
	v_cndmask_b32_sdwa v240, v1, v251, vcc dst_sel:DWORD dst_unused:UNUSED_PAD src0_sel:DWORD src1_sel:WORD_0
	v_cmp_lt_i32_e32 vcc, v197, v243
	v_lshl_add_u32 v246, v240, 8, v253
	global_load_dwordx4 v[130:133], v246, s[12:13]
	v_cndmask_b32_sdwa v240, v1, v251, vcc dst_sel:DWORD dst_unused:UNUSED_PAD src0_sel:DWORD src1_sel:WORD_1
	v_lshl_add_u32 v247, v240, 8, v253
	global_load_dwordx4 v[134:137], v247, s[12:13]
; #define MFMA16(a, b, c) __builtin_amdgcn_mfma_f32_16x16x32_bf16((a), (b), (c), 0, 0, 0)
; DI void dsa_item(const Params& p, int b, int blk) {
;     ...
;       const bf16x8 pa = *(const bf16x8*)(Pb + arow * PSTR + kc * 32 + g16 * 8);
;       u32x2 t0[8], t1[8];
;       asm volatile(
;           "s_waitcnt lgkmcnt(0)\n\t"
;           "ds_read_b64_tr_b16 %0, %16\n\tds_read_b64_tr_b16 %1, %17\n\tds_read_b64_tr_b16 %2, %18\n\tds_read_b64_tr_b16 %3, %19\n\t"
;           "ds_read_b64_tr_b16 %4, %20\n\tds_read_b64_tr_b16 %5, %21\n\tds_read_b64_tr_b16 %6, %22\n\tds_read_b64_tr_b16 %7, %23\n\t"
;           "ds_read_b64_tr_b16 %8, %24\n\tds_read_b64_tr_b16 %9, %25\n\tds_read_b64_tr_b16 %10, %26\n\tds_read_b64_tr_b16 %11, %27\n\t"
;           "ds_read_b64_tr_b16 %12, %28\n\tds_read_b64_tr_b16 %13, %29\n\tds_read_b64_tr_b16 %14, %30\n\tds_read_b64_tr_b16 %15, %31\n\t"
;           "s_waitcnt lgkmcnt(0)"
;           : "=&v"(t0[0]), "=&v"(t1[0]), "=&v"(t0[1]), "=&v"(t1[1]), "=&v"(t0[2]), "=&v"(t1[2]), "=&v"(t0[3]), "=&v"(t1[3]),
;             "=&v"(t0[4]), "=&v"(t1[4]), "=&v"(t0[5]), "=&v"(t1[5]), "=&v"(t0[6]), "=&v"(t1[6]), "=&v"(t0[7]), "=&v"(t1[7])
;           : "v"(lds_base + taddr[0][0]), "v"(lds_base + taddr[0][1]), "v"(lds_base + taddr[1][0]), "v"(lds_base + taddr[1][1]),
;             "v"(lds_base + taddr[2][0]), "v"(lds_base + taddr[2][1]), "v"(lds_base + taddr[3][0]), "v"(lds_base + taddr[3][1]),
;             "v"(lds_base + taddr[4][0]), "v"(lds_base + taddr[4][1]), "v"(lds_base + taddr[5][0]), "v"(lds_base + taddr[5][1]),
;             "v"(lds_base + taddr[6][0]), "v"(lds_base + taddr[6][1]), "v"(lds_base + taddr[7][0]), "v"(lds_base + taddr[7][1])
;           : "memory");
;       #pragma unroll
;       for (int c = 0; c < 8; ++c) {
;         u32x4 bv; bv[0] = t0[c][0]; bv[1] = t0[c][1]; bv[2] = t1[c][0]; bv[3] = t1[c][1];
;         oacc[c] = MFMA16(pa, __builtin_bit_cast(bf16x8, bv), oacc[c]);
;       }
;     }
.Lgv7_done:
	ds_read_b128 v[70:73], v68 offset:256
	s_waitcnt lgkmcnt(0)
	ds_read_b64_tr_b16 v[102:103], v162
	ds_read_b64_tr_b16 v[104:105], v163
	ds_read_b64_tr_b16 v[98:99], v164
	ds_read_b64_tr_b16 v[100:101], v165
	ds_read_b64_tr_b16 v[94:95], v166
	ds_read_b64_tr_b16 v[96:97], v167
	ds_read_b64_tr_b16 v[90:91], v168
	ds_read_b64_tr_b16 v[92:93], v169
	ds_read_b64_tr_b16 v[86:87], v170
	ds_read_b64_tr_b16 v[88:89], v171
	ds_read_b64_tr_b16 v[82:83], v172
	ds_read_b64_tr_b16 v[84:85], v173
	ds_read_b64_tr_b16 v[78:79], v174
	ds_read_b64_tr_b16 v[80:81], v175
	ds_read_b64_tr_b16 v[74:75], v176
	ds_read_b64_tr_b16 v[76:77], v177
	s_waitcnt lgkmcnt(0)
	v_mfma_f32_16x16x32_bf16 v[50:53], v[70:73], v[102:105], v[50:53]
	v_mfma_f32_16x16x32_bf16 v[38:41], v[70:73], v[98:101], v[38:41]
	v_mfma_f32_16x16x32_bf16 v[30:33], v[70:73], v[94:97], v[30:33]
	v_mfma_f32_16x16x32_bf16 v[18:21], v[70:73], v[90:93], v[18:21]
	v_mfma_f32_16x16x32_bf16 v[42:45], v[70:73], v[86:89], v[42:45]
	v_mfma_f32_16x16x32_bf16 v[26:29], v[70:73], v[82:85], v[26:29]
	v_mfma_f32_16x16x32_bf16 v[14:17], v[70:73], v[78:81], v[14:17]
	v_mfma_f32_16x16x32_bf16 v[6:9], v[70:73], v[74:77], v[6:9]
	s_waitcnt vmcnt(16)
	ds_write_b128 v198, v[2:5]
	ds_write_b128 v199, v[10:13]
	ds_write_b128 v200, v[22:25]
	ds_write_b128 v201, v[34:37]
	ds_write_b128 v202, v[46:49]
	ds_write_b128 v203, v[54:57]
	ds_write_b128 v204, v[58:61]
	ds_write_b128 v205, v[62:65]
	ds_read_b128 v[70:73], v68 offset:320
	s_waitcnt lgkmcnt(0)
	ds_read_b64_tr_b16 v[102:103], v162
	ds_read_b64_tr_b16 v[104:105], v163
	ds_read_b64_tr_b16 v[98:99], v164
	ds_read_b64_tr_b16 v[100:101], v165
	ds_read_b64_tr_b16 v[94:95], v166
	ds_read_b64_tr_b16 v[96:97], v167
	ds_read_b64_tr_b16 v[90:91], v168
	ds_read_b64_tr_b16 v[92:93], v169
	ds_read_b64_tr_b16 v[86:87], v170
	ds_read_b64_tr_b16 v[88:89], v171
	ds_read_b64_tr_b16 v[82:83], v172
	ds_read_b64_tr_b16 v[84:85], v173
	ds_read_b64_tr_b16 v[78:79], v174
	ds_read_b64_tr_b16 v[80:81], v175
	ds_read_b64_tr_b16 v[74:75], v176
	ds_read_b64_tr_b16 v[76:77], v177
	s_waitcnt lgkmcnt(0)
	v_mfma_f32_16x16x32_bf16 v[50:53], v[70:73], v[102:105], v[50:53]
	v_mfma_f32_16x16x32_bf16 v[38:41], v[70:73], v[98:101], v[38:41]
	v_mfma_f32_16x16x32_bf16 v[30:33], v[70:73], v[94:97], v[30:33]
	v_mfma_f32_16x16x32_bf16 v[18:21], v[70:73], v[90:93], v[18:21]
	v_mfma_f32_16x16x32_bf16 v[42:45], v[70:73], v[86:89], v[42:45]
	v_mfma_f32_16x16x32_bf16 v[26:29], v[70:73], v[82:85], v[26:29]
	v_mfma_f32_16x16x32_bf16 v[14:17], v[70:73], v[78:81], v[14:17]
	v_mfma_f32_16x16x32_bf16 v[6:9], v[70:73], v[74:77], v[6:9]
	s_waitcnt vmcnt(8)
	ds_write_b128 v198, v[208:211]
	ds_write_b128 v199, v[212:215]
	ds_write_b128 v200, v[216:219]
	ds_write_b128 v201, v[220:223]
	ds_write_b128 v202, v[224:227]
	ds_write_b128 v203, v[228:231]
	ds_write_b128 v204, v[232:235]
	ds_write_b128 v205, v[236:239]
	ds_read_b128 v[70:73], v68 offset:384
	s_waitcnt lgkmcnt(0)
	ds_read_b64_tr_b16 v[102:103], v162
	ds_read_b64_tr_b16 v[104:105], v163
	ds_read_b64_tr_b16 v[98:99], v164
	ds_read_b64_tr_b16 v[100:101], v165
	ds_read_b64_tr_b16 v[94:95], v166
	ds_read_b64_tr_b16 v[96:97], v167
	ds_read_b64_tr_b16 v[90:91], v168
	ds_read_b64_tr_b16 v[92:93], v169
	ds_read_b64_tr_b16 v[86:87], v170
	ds_read_b64_tr_b16 v[88:89], v171
	ds_read_b64_tr_b16 v[82:83], v172
	ds_read_b64_tr_b16 v[84:85], v173
	ds_read_b64_tr_b16 v[78:79], v174
	ds_read_b64_tr_b16 v[80:81], v175
	ds_read_b64_tr_b16 v[74:75], v176
	ds_read_b64_tr_b16 v[76:77], v177
	s_waitcnt lgkmcnt(0)
	v_mfma_f32_16x16x32_bf16 v[50:53], v[70:73], v[102:105], v[50:53]
	v_mfma_f32_16x16x32_bf16 v[38:41], v[70:73], v[98:101], v[38:41]
	v_mfma_f32_16x16x32_bf16 v[30:33], v[70:73], v[94:97], v[30:33]
	v_mfma_f32_16x16x32_bf16 v[18:21], v[70:73], v[90:93], v[18:21]
	v_mfma_f32_16x16x32_bf16 v[42:45], v[70:73], v[86:89], v[42:45]
	v_mfma_f32_16x16x32_bf16 v[26:29], v[70:73], v[82:85], v[26:29]
	v_mfma_f32_16x16x32_bf16 v[14:17], v[70:73], v[78:81], v[14:17]
	v_mfma_f32_16x16x32_bf16 v[6:9], v[70:73], v[74:77], v[6:9]
	s_waitcnt vmcnt(0)
	ds_write_b128 v198, v[106:109]
	ds_write_b128 v199, v[110:113]
	ds_write_b128 v200, v[114:117]
	ds_write_b128 v201, v[118:121]
	ds_write_b128 v202, v[122:125]
	ds_write_b128 v203, v[126:129]
	ds_write_b128 v204, v[130:133]
	ds_write_b128 v205, v[134:137]
	ds_read_b128 v[70:73], v68 offset:448
	s_waitcnt lgkmcnt(0)
	ds_read_b64_tr_b16 v[102:103], v162
	ds_read_b64_tr_b16 v[104:105], v163
	ds_read_b64_tr_b16 v[98:99], v164
	ds_read_b64_tr_b16 v[100:101], v165
	ds_read_b64_tr_b16 v[94:95], v166
	ds_read_b64_tr_b16 v[96:97], v167
	ds_read_b64_tr_b16 v[90:91], v168
	ds_read_b64_tr_b16 v[92:93], v169
	ds_read_b64_tr_b16 v[86:87], v170
	ds_read_b64_tr_b16 v[88:89], v171
	ds_read_b64_tr_b16 v[82:83], v172
	ds_read_b64_tr_b16 v[84:85], v173
	ds_read_b64_tr_b16 v[78:79], v174
	ds_read_b64_tr_b16 v[80:81], v175
	ds_read_b64_tr_b16 v[74:75], v176
	ds_read_b64_tr_b16 v[76:77], v177
	s_waitcnt lgkmcnt(0)
	v_mfma_f32_16x16x32_bf16 v[50:53], v[70:73], v[102:105], v[50:53]
	v_mfma_f32_16x16x32_bf16 v[38:41], v[70:73], v[98:101], v[38:41]
	v_mfma_f32_16x16x32_bf16 v[30:33], v[70:73], v[94:97], v[30:33]
	v_mfma_f32_16x16x32_bf16 v[18:21], v[70:73], v[90:93], v[18:21]
	v_mfma_f32_16x16x32_bf16 v[42:45], v[70:73], v[86:89], v[42:45]
	v_mfma_f32_16x16x32_bf16 v[26:29], v[70:73], v[82:85], v[26:29]
	v_mfma_f32_16x16x32_bf16 v[14:17], v[70:73], v[78:81], v[14:17]
	v_mfma_f32_16x16x32_bf16 v[6:9], v[70:73], v[74:77], v[6:9]
	s_nop 0
